# rstd table: issue all row-statistic loads before one wait; relaxed first-tile waits also after in-proj epilogue
# speedup vs baseline: 1.0119x; 1.0055x over previous
; #define LAS __attribute__((address_space(3)))
;     __host__ __device__ bool next(int i, Unit& u) const {
;         const long L = (long)i * G + c; if (L >= nwg) return false;
;         int wgid = (int)L; { const int q = nwg / NXCD, r = nwg % NXCD, xcd = wgid % NXCD, off = wgid / NXCD; wgid = (xcd < r ? xcd * (q + 1) : r * (q + 1) + (xcd - r) * q) + off; }
;         const int nig = WGM * nN, gid = wgid / nig, fm = gid * WGM, gsz = (nM - fm) < WGM ? (nM - fm) : WGM;
;         u.pm = fm + ((wgid % nig) % gsz); u.pn = (wgid % nig) / gsz; u.idx = i; return true;
; template <class Sched>
; __device__ __forceinline__ void rstd_table(LAS float* rs, const float* ss, const Sched& S) {
;     Unit u;
;     for (int i = 0; i < 15 && S.next(i, u); ++i) if (threadIdx.x < BM) rs[i * BM + threadIdx.x] = rsqrtf(ss[u.pm * BM + threadIdx.x] * (1.0f / DM) + NORM_EPS);
; }
.LBB0_552:
	v_writelane_b32 v245, s96, 10
	s_xor_b64 s[0:1], s[4:5], -1
	v_writelane_b32 v245, s0, 11
	s_cmp_lt_i32 s88, 2
	s_nop 0
	v_writelane_b32 v245, s1, 12
	s_cselect_b64 s[0:1], -1, 0
	v_readlane_b32 s81, v245, 0
	s_lshl_b32 s6, s81, 3
	s_or_b32 s8, s6, s92
	s_and_b64 s[6:7], s[4:5], exec
	s_cselect_b32 s97, s8, s95
	s_add_u32 s68, s74, 0x7800000
	s_addc_u32 s69, s75, 0
	s_mul_i32 s6, s92, 0xe00000
	s_and_b64 s[4:5], s[4:5], exec
	s_cselect_b32 s5, s6, 0
	s_cselect_b32 s4, 0, 0
	s_add_u32 s64, s68, s5
	s_addc_u32 s65, s69, s4
	s_and_b64 s[0:1], s[0:1], s[2:3]
	s_andn2_b64 vcc, exec, s[0:1]
	s_mov_b64 s[4:5], -1
	s_cbranch_vccnz .LBB0_614
	s_ashr_i32 s0, s76, 31
	s_ashr_i32 s1, s97, 31
	s_cmpk_lt_i32 s97, 0xb00
	s_cselect_b64 s[6:7], -1, 0
	s_cmpk_gt_i32 s97, 0xaff
	s_cbranch_scc1 .LBB0_598
	s_movk_i32 s2, 0x100
	s_add_i32 s8, 0, 0x20000
	v_cmp_gt_u32_e64 s[2:3], s2, v153
	s_waitcnt vmcnt(4)
	v_lshl_add_u32 v0, v153, 2, s8
	s_and_saveexec_b64 s[8:9], s[2:3]
	s_cbranch_execz .LBB0_556
	s_lshr_b32 s10, s1, 29
	s_add_i32 s10, s97, s10
	s_and_b32 s11, s10, -8
	s_sub_i32 s11, s97, s11
	s_cmp_lt_i32 s11, 0
	s_movk_i32 s12, 0x161
	s_cselect_b32 s12, s12, 0x160
	s_mul_i32 s11, s11, s12
	s_ashr_i32 s10, s10, 3
	s_add_i32 s11, s11, s10
	s_mul_hi_i32 s10, s11, 0x2e8ba2e9
	s_lshr_b32 s12, s10, 31
	s_ashr_i32 s10, s10, 4
	s_add_i32 s10, s10, s12
	s_lshl_b32 s12, s10, 2
	s_sub_i32 s13, 0x80, s12
	s_min_i32 s13, s13, 4
	s_abs_i32 s13, s13
	v_cvt_f32_u32_e32 v1, s13
	s_sub_i32 s14, 0, s13
	s_mulk_i32 s10, 0x58
	s_sub_i32 s10, s11, s10
	v_rcp_iflag_f32_e32 v1, v1
	s_ashr_i32 s11, s10, 31
	s_abs_i32 s10, s10
	v_mov_b32_e32 v3, 0
	v_mul_f32_e32 v1, 0x4f7ffffe, v1
	v_cvt_u32_f32_e32 v1, v1
	s_nop 0
	v_readfirstlane_b32 s15, v1
	s_mul_i32 s14, s14, s15
	s_mul_hi_u32 s14, s15, s14
	s_add_i32 s15, s15, s14
	s_mul_hi_u32 s14, s10, s15
	s_mul_i32 s14, s14, s13
	s_sub_i32 s10, s10, s14
	s_sub_i32 s14, s10, s13
	s_cmp_ge_u32 s10, s13
	s_cselect_b32 s10, s14, s10
	s_sub_i32 s14, s10, s13
	s_cmp_ge_u32 s10, s13
	s_cselect_b32 s10, s14, s10
	s_xor_b32 s10, s10, s11
	s_sub_i32 s10, s10, s11
	s_add_i32 s10, s10, s12
	v_lshl_or_b32 v2, s10, 8, v153
	v_lshl_add_u64 v[2:3], v[2:3], 2, s[24:25]
	global_load_dword v100, v[2:3], off
.LBB0_556:
	s_or_b64 exec, exec, s[8:9]
	s_add_u32 s8, s76, s97
	s_addc_u32 s9, s0, s1
	v_mov_b64_e32 v[2:3], 0xaff
	v_cmp_gt_i64_e32 vcc, s[8:9], v[2:3]
	s_cbranch_vccnz .LBB0_598
	s_and_saveexec_b64 s[10:11], s[2:3]
	s_cbranch_execz .LBB0_559
	s_ashr_i32 s12, s8, 31
	s_lshr_b32 s12, s12, 29
	s_add_i32 s12, s8, s12
	s_ashr_i32 s13, s12, 3
	s_and_b32 s12, s12, -8
	s_sub_i32 s12, s8, s12
	s_cmp_lt_i32 s12, 0
	s_movk_i32 s14, 0x161
	s_cselect_b32 s14, s14, 0x160
	s_mul_i32 s12, s12, s14
	s_add_i32 s12, s12, s13
	s_mul_hi_i32 s13, s12, 0x2e8ba2e9
	s_lshr_b32 s14, s13, 31
	s_ashr_i32 s13, s13, 4
	s_add_i32 s13, s13, s14
	s_lshl_b32 s14, s13, 2
	s_sub_i32 s15, 0x80, s14
	s_min_i32 s15, s15, 4
	s_abs_i32 s15, s15
	v_cvt_f32_u32_e32 v1, s15
	s_sub_i32 s16, 0, s15
	s_mulk_i32 s13, 0x58
	s_sub_i32 s12, s12, s13
	v_rcp_iflag_f32_e32 v1, v1
	s_ashr_i32 s13, s12, 31
	s_abs_i32 s12, s12
	v_mov_b32_e32 v3, 0
	v_mul_f32_e32 v1, 0x4f7ffffe, v1
	v_cvt_u32_f32_e32 v1, v1
	s_nop 0
	v_readfirstlane_b32 s17, v1
	s_mul_i32 s16, s16, s17
	s_mul_hi_u32 s16, s17, s16
	s_add_i32 s17, s17, s16
	s_mul_hi_u32 s16, s12, s17
	s_mul_i32 s16, s16, s15
	s_sub_i32 s12, s12, s16
	s_sub_i32 s16, s12, s15
	s_cmp_ge_u32 s12, s15
	s_cselect_b32 s12, s16, s12
	s_sub_i32 s16, s12, s15
	s_cmp_ge_u32 s12, s15
	s_cselect_b32 s12, s16, s12
	s_xor_b32 s12, s12, s13
	s_sub_i32 s12, s12, s13
	s_add_i32 s12, s12, s14
	v_lshl_or_b32 v2, s12, 8, v153
	v_lshl_add_u64 v[2:3], v[2:3], 2, s[24:25]
	global_load_dword v101, v[2:3], off
.LBB0_559:
	s_or_b64 exec, exec, s[10:11]
	s_add_u32 s8, s8, s76
	s_addc_u32 s9, s9, s0
	v_mov_b64_e32 v[2:3], 0xaff
	v_cmp_gt_i64_e32 vcc, s[8:9], v[2:3]
	s_cbranch_vccnz .LBB0_598
	s_and_saveexec_b64 s[10:11], s[2:3]
	s_cbranch_execz .LBB0_562
	s_ashr_i32 s12, s8, 31
	s_lshr_b32 s12, s12, 29
	s_add_i32 s12, s8, s12
	s_ashr_i32 s13, s12, 3
	s_and_b32 s12, s12, -8
	s_sub_i32 s12, s8, s12
	s_cmp_lt_i32 s12, 0
	s_movk_i32 s14, 0x161
	s_cselect_b32 s14, s14, 0x160
	s_mul_i32 s12, s12, s14
	s_add_i32 s12, s12, s13
	s_mul_hi_i32 s13, s12, 0x2e8ba2e9
	s_lshr_b32 s14, s13, 31
	s_ashr_i32 s13, s13, 4
	s_add_i32 s13, s13, s14
	s_lshl_b32 s14, s13, 2
	s_sub_i32 s15, 0x80, s14
	s_min_i32 s15, s15, 4
	s_abs_i32 s15, s15
	v_cvt_f32_u32_e32 v1, s15
	s_sub_i32 s16, 0, s15
	s_mulk_i32 s13, 0x58
	s_sub_i32 s12, s12, s13
	v_rcp_iflag_f32_e32 v1, v1
	s_ashr_i32 s13, s12, 31
	s_abs_i32 s12, s12
	v_mov_b32_e32 v3, 0
	v_mul_f32_e32 v1, 0x4f7ffffe, v1
	v_cvt_u32_f32_e32 v1, v1
	s_nop 0
	v_readfirstlane_b32 s17, v1
	s_mul_i32 s16, s16, s17
	s_mul_hi_u32 s16, s17, s16
	s_add_i32 s17, s17, s16
	s_mul_hi_u32 s16, s12, s17
	s_mul_i32 s16, s16, s15
	s_sub_i32 s12, s12, s16
	s_sub_i32 s16, s12, s15
	s_cmp_ge_u32 s12, s15
	s_cselect_b32 s12, s16, s12
	s_sub_i32 s16, s12, s15
	s_cmp_ge_u32 s12, s15
	s_cselect_b32 s12, s16, s12
	s_xor_b32 s12, s12, s13
	s_sub_i32 s12, s12, s13
	s_add_i32 s12, s12, s14
	v_lshl_or_b32 v2, s12, 8, v153
	v_lshl_add_u64 v[2:3], v[2:3], 2, s[24:25]
	global_load_dword v102, v[2:3], off
; #define LAS __attribute__((address_space(3)))
;     __host__ __device__ bool next(int i, Unit& u) const {
;         const long L = (long)i * G + c; if (L >= nwg) return false;
;         int wgid = (int)L; { const int q = nwg / NXCD, r = nwg % NXCD, xcd = wgid % NXCD, off = wgid / NXCD; wgid = (xcd < r ? xcd * (q + 1) : r * (q + 1) + (xcd - r) * q) + off; }
;         const int nig = WGM * nN, gid = wgid / nig, fm = gid * WGM, gsz = (nM - fm) < WGM ? (nM - fm) : WGM;
;         u.pm = fm + ((wgid % nig) % gsz); u.pn = (wgid % nig) / gsz; u.idx = i; return true;
; template <class Sched>
; __device__ __forceinline__ void rstd_table(LAS float* rs, const float* ss, const Sched& S) {
;     Unit u;
;     for (int i = 0; i < 15 && S.next(i, u); ++i) if (threadIdx.x < BM) rs[i * BM + threadIdx.x] = rsqrtf(ss[u.pm * BM + threadIdx.x] * (1.0f / DM) + NORM_EPS);
; }
.LBB0_562:
	s_or_b64 exec, exec, s[10:11]
	s_add_u32 s8, s8, s76
	s_addc_u32 s9, s9, s0
	v_mov_b64_e32 v[2:3], 0xaff
	v_cmp_gt_i64_e32 vcc, s[8:9], v[2:3]
	s_cbranch_vccnz .LBB0_598
	s_and_saveexec_b64 s[10:11], s[2:3]
	s_cbranch_execz .LBB0_565
	s_ashr_i32 s12, s8, 31
	s_lshr_b32 s12, s12, 29
	s_add_i32 s12, s8, s12
	s_ashr_i32 s13, s12, 3
	s_and_b32 s12, s12, -8
	s_sub_i32 s12, s8, s12
	s_cmp_lt_i32 s12, 0
	s_movk_i32 s14, 0x161
	s_cselect_b32 s14, s14, 0x160
	s_mul_i32 s12, s12, s14
	s_add_i32 s12, s12, s13
	s_mul_hi_i32 s13, s12, 0x2e8ba2e9
	s_lshr_b32 s14, s13, 31
	s_ashr_i32 s13, s13, 4
	s_add_i32 s13, s13, s14
	s_lshl_b32 s14, s13, 2
	s_sub_i32 s15, 0x80, s14
	s_min_i32 s15, s15, 4
	s_abs_i32 s15, s15
	v_cvt_f32_u32_e32 v1, s15
	s_sub_i32 s16, 0, s15
	s_mulk_i32 s13, 0x58
	s_sub_i32 s12, s12, s13
	v_rcp_iflag_f32_e32 v1, v1
	s_ashr_i32 s13, s12, 31
	s_abs_i32 s12, s12
	v_mov_b32_e32 v3, 0
	v_mul_f32_e32 v1, 0x4f7ffffe, v1
	v_cvt_u32_f32_e32 v1, v1
	s_nop 0
	v_readfirstlane_b32 s17, v1
	s_mul_i32 s16, s16, s17
	s_mul_hi_u32 s16, s17, s16
	s_add_i32 s17, s17, s16
	s_mul_hi_u32 s16, s12, s17
	s_mul_i32 s16, s16, s15
	s_sub_i32 s12, s12, s16
	s_sub_i32 s16, s12, s15
	s_cmp_ge_u32 s12, s15
	s_cselect_b32 s12, s16, s12
	s_sub_i32 s16, s12, s15
	s_cmp_ge_u32 s12, s15
	s_cselect_b32 s12, s16, s12
	s_xor_b32 s12, s12, s13
	s_sub_i32 s12, s12, s13
	s_add_i32 s12, s12, s14
	v_lshl_or_b32 v2, s12, 8, v153
	v_lshl_add_u64 v[2:3], v[2:3], 2, s[24:25]
	global_load_dword v103, v[2:3], off
.LBB0_565:
	s_or_b64 exec, exec, s[10:11]
	s_add_u32 s8, s8, s76
	s_addc_u32 s9, s9, s0
	v_mov_b64_e32 v[2:3], 0xaff
	v_cmp_gt_i64_e32 vcc, s[8:9], v[2:3]
	s_cbranch_vccnz .LBB0_598
	s_and_saveexec_b64 s[10:11], s[2:3]
	s_cbranch_execz .LBB0_568
	s_ashr_i32 s12, s8, 31
	s_lshr_b32 s12, s12, 29
	s_add_i32 s12, s8, s12
	s_ashr_i32 s13, s12, 3
	s_and_b32 s12, s12, -8
	s_sub_i32 s12, s8, s12
	s_cmp_lt_i32 s12, 0
	s_movk_i32 s14, 0x161
	s_cselect_b32 s14, s14, 0x160
	s_mul_i32 s12, s12, s14
	s_add_i32 s12, s12, s13
	s_mul_hi_i32 s13, s12, 0x2e8ba2e9
	s_lshr_b32 s14, s13, 31
	s_ashr_i32 s13, s13, 4
	s_add_i32 s13, s13, s14
	s_lshl_b32 s14, s13, 2
	s_sub_i32 s15, 0x80, s14
	s_min_i32 s15, s15, 4
	s_abs_i32 s15, s15
	v_cvt_f32_u32_e32 v1, s15
	s_sub_i32 s16, 0, s15
	s_mulk_i32 s13, 0x58
	s_sub_i32 s12, s12, s13
	v_rcp_iflag_f32_e32 v1, v1
	s_ashr_i32 s13, s12, 31
	s_abs_i32 s12, s12
	v_mov_b32_e32 v3, 0
	v_mul_f32_e32 v1, 0x4f7ffffe, v1
	v_cvt_u32_f32_e32 v1, v1
	s_nop 0
	v_readfirstlane_b32 s17, v1
	s_mul_i32 s16, s16, s17
	s_mul_hi_u32 s16, s17, s16
	s_add_i32 s17, s17, s16
	s_mul_hi_u32 s16, s12, s17
	s_mul_i32 s16, s16, s15
	s_sub_i32 s12, s12, s16
	s_sub_i32 s16, s12, s15
	s_cmp_ge_u32 s12, s15
	s_cselect_b32 s12, s16, s12
	s_sub_i32 s16, s12, s15
	s_cmp_ge_u32 s12, s15
	s_cselect_b32 s12, s16, s12
	s_xor_b32 s12, s12, s13
	s_sub_i32 s12, s12, s13
	s_add_i32 s12, s12, s14
	v_lshl_or_b32 v2, s12, 8, v153
	v_lshl_add_u64 v[2:3], v[2:3], 2, s[24:25]
	global_load_dword v104, v[2:3], off
.LBB0_568:
	s_or_b64 exec, exec, s[10:11]
	s_add_u32 s8, s8, s76
	s_addc_u32 s9, s9, s0
	v_mov_b64_e32 v[2:3], 0xaff
	v_cmp_gt_i64_e32 vcc, s[8:9], v[2:3]
	s_cbranch_vccnz .LBB0_598
	s_and_saveexec_b64 s[10:11], s[2:3]
	s_cbranch_execz .LBB0_571
	s_ashr_i32 s12, s8, 31
	s_lshr_b32 s12, s12, 29
	s_add_i32 s12, s8, s12
	s_ashr_i32 s13, s12, 3
	s_and_b32 s12, s12, -8
	s_sub_i32 s12, s8, s12
	s_cmp_lt_i32 s12, 0
	s_movk_i32 s14, 0x161
	s_cselect_b32 s14, s14, 0x160
	s_mul_i32 s12, s12, s14
	s_add_i32 s12, s12, s13
	s_mul_hi_i32 s13, s12, 0x2e8ba2e9
	s_lshr_b32 s14, s13, 31
	s_ashr_i32 s13, s13, 4
	s_add_i32 s13, s13, s14
	s_lshl_b32 s14, s13, 2
	s_sub_i32 s15, 0x80, s14
	s_min_i32 s15, s15, 4
	s_abs_i32 s15, s15
	v_cvt_f32_u32_e32 v1, s15
	s_sub_i32 s16, 0, s15
	s_mulk_i32 s13, 0x58
	s_sub_i32 s12, s12, s13
	v_rcp_iflag_f32_e32 v1, v1
	s_ashr_i32 s13, s12, 31
	s_abs_i32 s12, s12
	v_mov_b32_e32 v3, 0
	v_mul_f32_e32 v1, 0x4f7ffffe, v1
	v_cvt_u32_f32_e32 v1, v1
	s_nop 0
	v_readfirstlane_b32 s17, v1
	s_mul_i32 s16, s16, s17
	s_mul_hi_u32 s16, s17, s16
	s_add_i32 s17, s17, s16
	s_mul_hi_u32 s16, s12, s17
	s_mul_i32 s16, s16, s15
	s_sub_i32 s12, s12, s16
	s_sub_i32 s16, s12, s15
	s_cmp_ge_u32 s12, s15
	s_cselect_b32 s12, s16, s12
	s_sub_i32 s16, s12, s15
	s_cmp_ge_u32 s12, s15
	s_cselect_b32 s12, s16, s12
	s_xor_b32 s12, s12, s13
	s_sub_i32 s12, s12, s13
	s_add_i32 s12, s12, s14
	v_lshl_or_b32 v2, s12, 8, v153
	v_lshl_add_u64 v[2:3], v[2:3], 2, s[24:25]
	global_load_dword v105, v[2:3], off
.LBB0_571:
	s_or_b64 exec, exec, s[10:11]
	s_add_u32 s8, s8, s76
	s_addc_u32 s9, s9, s0
	v_mov_b64_e32 v[2:3], 0xaff
	v_cmp_gt_i64_e32 vcc, s[8:9], v[2:3]
	s_cbranch_vccnz .LBB0_598
	s_and_saveexec_b64 s[10:11], s[2:3]
	s_cbranch_execz .LBB0_574
	s_ashr_i32 s12, s8, 31
	s_lshr_b32 s12, s12, 29
	s_add_i32 s12, s8, s12
	s_ashr_i32 s13, s12, 3
	s_and_b32 s12, s12, -8
	s_sub_i32 s12, s8, s12
	s_cmp_lt_i32 s12, 0
	s_movk_i32 s14, 0x161
	s_cselect_b32 s14, s14, 0x160
	s_mul_i32 s12, s12, s14
	s_add_i32 s12, s12, s13
	s_mul_hi_i32 s13, s12, 0x2e8ba2e9
	s_lshr_b32 s14, s13, 31
	s_ashr_i32 s13, s13, 4
	s_add_i32 s13, s13, s14
	s_lshl_b32 s14, s13, 2
	s_sub_i32 s15, 0x80, s14
	s_min_i32 s15, s15, 4
	s_abs_i32 s15, s15
	v_cvt_f32_u32_e32 v1, s15
	s_sub_i32 s16, 0, s15
	s_mulk_i32 s13, 0x58
	s_sub_i32 s12, s12, s13
	v_rcp_iflag_f32_e32 v1, v1
	s_ashr_i32 s13, s12, 31
	s_abs_i32 s12, s12
	v_mov_b32_e32 v3, 0
	v_mul_f32_e32 v1, 0x4f7ffffe, v1
	v_cvt_u32_f32_e32 v1, v1
	s_nop 0
	v_readfirstlane_b32 s17, v1
	s_mul_i32 s16, s16, s17
	s_mul_hi_u32 s16, s17, s16
	s_add_i32 s17, s17, s16
	s_mul_hi_u32 s16, s12, s17
	s_mul_i32 s16, s16, s15
	s_sub_i32 s12, s12, s16
	s_sub_i32 s16, s12, s15
	s_cmp_ge_u32 s12, s15
	s_cselect_b32 s12, s16, s12
	s_sub_i32 s16, s12, s15
	s_cmp_ge_u32 s12, s15
	s_cselect_b32 s12, s16, s12
	s_xor_b32 s12, s12, s13
	s_sub_i32 s12, s12, s13
	s_add_i32 s12, s12, s14
	v_lshl_or_b32 v2, s12, 8, v153
	v_lshl_add_u64 v[2:3], v[2:3], 2, s[24:25]
	global_load_dword v106, v[2:3], off
; #define LAS __attribute__((address_space(3)))
;     __host__ __device__ bool next(int i, Unit& u) const {
;         const long L = (long)i * G + c; if (L >= nwg) return false;
;         int wgid = (int)L; { const int q = nwg / NXCD, r = nwg % NXCD, xcd = wgid % NXCD, off = wgid / NXCD; wgid = (xcd < r ? xcd * (q + 1) : r * (q + 1) + (xcd - r) * q) + off; }
;         const int nig = WGM * nN, gid = wgid / nig, fm = gid * WGM, gsz = (nM - fm) < WGM ? (nM - fm) : WGM;
;         u.pm = fm + ((wgid % nig) % gsz); u.pn = (wgid % nig) / gsz; u.idx = i; return true;
; template <class Sched>
; __device__ __forceinline__ void rstd_table(LAS float* rs, const float* ss, const Sched& S) {
;     Unit u;
;     for (int i = 0; i < 15 && S.next(i, u); ++i) if (threadIdx.x < BM) rs[i * BM + threadIdx.x] = rsqrtf(ss[u.pm * BM + threadIdx.x] * (1.0f / DM) + NORM_EPS);
; }
.LBB0_574:
	s_or_b64 exec, exec, s[10:11]
	s_add_u32 s8, s8, s76
	s_addc_u32 s9, s9, s0
	v_mov_b64_e32 v[2:3], 0xaff
	v_cmp_gt_i64_e32 vcc, s[8:9], v[2:3]
	s_cbranch_vccnz .LBB0_598
	s_and_saveexec_b64 s[10:11], s[2:3]
	s_cbranch_execz .LBB0_577
	s_ashr_i32 s12, s8, 31
	s_lshr_b32 s12, s12, 29
	s_add_i32 s12, s8, s12
	s_ashr_i32 s13, s12, 3
	s_and_b32 s12, s12, -8
	s_sub_i32 s12, s8, s12
	s_cmp_lt_i32 s12, 0
	s_movk_i32 s14, 0x161
	s_cselect_b32 s14, s14, 0x160
	s_mul_i32 s12, s12, s14
	s_add_i32 s12, s12, s13
	s_mul_hi_i32 s13, s12, 0x2e8ba2e9
	s_lshr_b32 s14, s13, 31
	s_ashr_i32 s13, s13, 4
	s_add_i32 s13, s13, s14
	s_lshl_b32 s14, s13, 2
	s_sub_i32 s15, 0x80, s14
	s_min_i32 s15, s15, 4
	s_abs_i32 s15, s15
	v_cvt_f32_u32_e32 v1, s15
	s_sub_i32 s16, 0, s15
	s_mulk_i32 s13, 0x58
	s_sub_i32 s12, s12, s13
	v_rcp_iflag_f32_e32 v1, v1
	s_ashr_i32 s13, s12, 31
	s_abs_i32 s12, s12
	v_mov_b32_e32 v3, 0
	v_mul_f32_e32 v1, 0x4f7ffffe, v1
	v_cvt_u32_f32_e32 v1, v1
	s_nop 0
	v_readfirstlane_b32 s17, v1
	s_mul_i32 s16, s16, s17
	s_mul_hi_u32 s16, s17, s16
	s_add_i32 s17, s17, s16
	s_mul_hi_u32 s16, s12, s17
	s_mul_i32 s16, s16, s15
	s_sub_i32 s12, s12, s16
	s_sub_i32 s16, s12, s15
	s_cmp_ge_u32 s12, s15
	s_cselect_b32 s12, s16, s12
	s_sub_i32 s16, s12, s15
	s_cmp_ge_u32 s12, s15
	s_cselect_b32 s12, s16, s12
	s_xor_b32 s12, s12, s13
	s_sub_i32 s12, s12, s13
	s_add_i32 s12, s12, s14
	v_lshl_or_b32 v2, s12, 8, v153
	v_lshl_add_u64 v[2:3], v[2:3], 2, s[24:25]
	global_load_dword v107, v[2:3], off
.LBB0_577:
	s_or_b64 exec, exec, s[10:11]
	s_add_u32 s8, s8, s76
	s_addc_u32 s9, s9, s0
	v_mov_b64_e32 v[2:3], 0xaff
	v_cmp_gt_i64_e32 vcc, s[8:9], v[2:3]
	s_cbranch_vccnz .LBB0_598
	s_and_saveexec_b64 s[10:11], s[2:3]
	s_cbranch_execz .LBB0_580
	s_ashr_i32 s12, s8, 31
	s_lshr_b32 s12, s12, 29
	s_add_i32 s12, s8, s12
	s_ashr_i32 s13, s12, 3
	s_and_b32 s12, s12, -8
	s_sub_i32 s12, s8, s12
	s_cmp_lt_i32 s12, 0
	s_movk_i32 s14, 0x161
	s_cselect_b32 s14, s14, 0x160
	s_mul_i32 s12, s12, s14
	s_add_i32 s12, s12, s13
	s_mul_hi_i32 s13, s12, 0x2e8ba2e9
	s_lshr_b32 s14, s13, 31
	s_ashr_i32 s13, s13, 4
	s_add_i32 s13, s13, s14
	s_lshl_b32 s14, s13, 2
	s_sub_i32 s15, 0x80, s14
	s_min_i32 s15, s15, 4
	s_abs_i32 s15, s15
	v_cvt_f32_u32_e32 v1, s15
	s_sub_i32 s16, 0, s15
	s_mulk_i32 s13, 0x58
	s_sub_i32 s12, s12, s13
	v_rcp_iflag_f32_e32 v1, v1
	s_ashr_i32 s13, s12, 31
	s_abs_i32 s12, s12
	v_mov_b32_e32 v3, 0
	v_mul_f32_e32 v1, 0x4f7ffffe, v1
	v_cvt_u32_f32_e32 v1, v1
	s_nop 0
	v_readfirstlane_b32 s17, v1
	s_mul_i32 s16, s16, s17
	s_mul_hi_u32 s16, s17, s16
	s_add_i32 s17, s17, s16
	s_mul_hi_u32 s16, s12, s17
	s_mul_i32 s16, s16, s15
	s_sub_i32 s12, s12, s16
	s_sub_i32 s16, s12, s15
	s_cmp_ge_u32 s12, s15
	s_cselect_b32 s12, s16, s12
	s_sub_i32 s16, s12, s15
	s_cmp_ge_u32 s12, s15
	s_cselect_b32 s12, s16, s12
	s_xor_b32 s12, s12, s13
	s_sub_i32 s12, s12, s13
	s_add_i32 s12, s12, s14
	v_lshl_or_b32 v2, s12, 8, v153
	v_lshl_add_u64 v[2:3], v[2:3], 2, s[24:25]
	global_load_dword v108, v[2:3], off
.LBB0_580:
	s_or_b64 exec, exec, s[10:11]
	s_add_u32 s8, s8, s76
	s_addc_u32 s9, s9, s0
	v_mov_b64_e32 v[2:3], 0xaff
	v_cmp_gt_i64_e32 vcc, s[8:9], v[2:3]
	s_cbranch_vccnz .LBB0_598
	s_and_saveexec_b64 s[10:11], s[2:3]
	s_cbranch_execz .LBB0_583
	s_ashr_i32 s12, s8, 31
	s_lshr_b32 s12, s12, 29
	s_add_i32 s12, s8, s12
	s_ashr_i32 s13, s12, 3
	s_and_b32 s12, s12, -8
	s_sub_i32 s12, s8, s12
	s_cmp_lt_i32 s12, 0
	s_movk_i32 s14, 0x161
	s_cselect_b32 s14, s14, 0x160
	s_mul_i32 s12, s12, s14
	s_add_i32 s12, s12, s13
	s_mul_hi_i32 s13, s12, 0x2e8ba2e9
	s_lshr_b32 s14, s13, 31
	s_ashr_i32 s13, s13, 4
	s_add_i32 s13, s13, s14
	s_lshl_b32 s14, s13, 2
	s_sub_i32 s15, 0x80, s14
	s_min_i32 s15, s15, 4
	s_abs_i32 s15, s15
	v_cvt_f32_u32_e32 v1, s15
	s_sub_i32 s16, 0, s15
	s_mulk_i32 s13, 0x58
	s_sub_i32 s12, s12, s13
	v_rcp_iflag_f32_e32 v1, v1
	s_ashr_i32 s13, s12, 31
	s_abs_i32 s12, s12
	v_mov_b32_e32 v3, 0
	v_mul_f32_e32 v1, 0x4f7ffffe, v1
	v_cvt_u32_f32_e32 v1, v1
	s_nop 0
	v_readfirstlane_b32 s17, v1
	s_mul_i32 s16, s16, s17
	s_mul_hi_u32 s16, s17, s16
	s_add_i32 s17, s17, s16
	s_mul_hi_u32 s16, s12, s17
	s_mul_i32 s16, s16, s15
	s_sub_i32 s12, s12, s16
	s_sub_i32 s16, s12, s15
	s_cmp_ge_u32 s12, s15
	s_cselect_b32 s12, s16, s12
	s_sub_i32 s16, s12, s15
	s_cmp_ge_u32 s12, s15
	s_cselect_b32 s12, s16, s12
	s_xor_b32 s12, s12, s13
	s_sub_i32 s12, s12, s13
	s_add_i32 s12, s12, s14
	v_lshl_or_b32 v2, s12, 8, v153
	v_lshl_add_u64 v[2:3], v[2:3], 2, s[24:25]
	global_load_dword v109, v[2:3], off
.LBB0_583:
	s_or_b64 exec, exec, s[10:11]
	s_add_u32 s8, s8, s76
	s_addc_u32 s9, s9, s0
	v_mov_b64_e32 v[2:3], 0xaff
	v_cmp_gt_i64_e32 vcc, s[8:9], v[2:3]
	s_cbranch_vccnz .LBB0_598
	s_and_saveexec_b64 s[10:11], s[2:3]
	s_cbranch_execz .LBB0_586
	s_ashr_i32 s12, s8, 31
	s_lshr_b32 s12, s12, 29
	s_add_i32 s12, s8, s12
	s_ashr_i32 s13, s12, 3
	s_and_b32 s12, s12, -8
	s_sub_i32 s12, s8, s12
	s_cmp_lt_i32 s12, 0
	s_movk_i32 s14, 0x161
	s_cselect_b32 s14, s14, 0x160
	s_mul_i32 s12, s12, s14
	s_add_i32 s12, s12, s13
	s_mul_hi_i32 s13, s12, 0x2e8ba2e9
	s_lshr_b32 s14, s13, 31
	s_ashr_i32 s13, s13, 4
	s_add_i32 s13, s13, s14
	s_lshl_b32 s14, s13, 2
	s_sub_i32 s15, 0x80, s14
	s_min_i32 s15, s15, 4
	s_abs_i32 s15, s15
	v_cvt_f32_u32_e32 v1, s15
	s_sub_i32 s16, 0, s15
	s_mulk_i32 s13, 0x58
	s_sub_i32 s12, s12, s13
	v_rcp_iflag_f32_e32 v1, v1
	s_ashr_i32 s13, s12, 31
	s_abs_i32 s12, s12
	v_mov_b32_e32 v3, 0
	v_mul_f32_e32 v1, 0x4f7ffffe, v1
	v_cvt_u32_f32_e32 v1, v1
	s_nop 0
	v_readfirstlane_b32 s17, v1
	s_mul_i32 s16, s16, s17
	s_mul_hi_u32 s16, s17, s16
	s_add_i32 s17, s17, s16
	s_mul_hi_u32 s16, s12, s17
	s_mul_i32 s16, s16, s15
	s_sub_i32 s12, s12, s16
	s_sub_i32 s16, s12, s15
	s_cmp_ge_u32 s12, s15
	s_cselect_b32 s12, s16, s12
	s_sub_i32 s16, s12, s15
	s_cmp_ge_u32 s12, s15
	s_cselect_b32 s12, s16, s12
	s_xor_b32 s12, s12, s13
	s_sub_i32 s12, s12, s13
	s_add_i32 s12, s12, s14
	v_lshl_or_b32 v2, s12, 8, v153
	v_lshl_add_u64 v[2:3], v[2:3], 2, s[24:25]
	global_load_dword v110, v[2:3], off
; #define LAS __attribute__((address_space(3)))
;     __host__ __device__ bool next(int i, Unit& u) const {
;         const long L = (long)i * G + c; if (L >= nwg) return false;
;         int wgid = (int)L; { const int q = nwg / NXCD, r = nwg % NXCD, xcd = wgid % NXCD, off = wgid / NXCD; wgid = (xcd < r ? xcd * (q + 1) : r * (q + 1) + (xcd - r) * q) + off; }
;         const int nig = WGM * nN, gid = wgid / nig, fm = gid * WGM, gsz = (nM - fm) < WGM ? (nM - fm) : WGM;
;         u.pm = fm + ((wgid % nig) % gsz); u.pn = (wgid % nig) / gsz; u.idx = i; return true;
; template <class Sched>
; __device__ __forceinline__ void rstd_table(LAS float* rs, const float* ss, const Sched& S) {
;     Unit u;
;     for (int i = 0; i < 15 && S.next(i, u); ++i) if (threadIdx.x < BM) rs[i * BM + threadIdx.x] = rsqrtf(ss[u.pm * BM + threadIdx.x] * (1.0f / DM) + NORM_EPS);
; }
.LBB0_586:
	s_or_b64 exec, exec, s[10:11]
	s_add_u32 s8, s8, s76
	s_addc_u32 s9, s9, s0
	v_mov_b64_e32 v[2:3], 0xaff
	v_cmp_gt_i64_e32 vcc, s[8:9], v[2:3]
	s_cbranch_vccnz .LBB0_598
	s_and_saveexec_b64 s[10:11], s[2:3]
	s_cbranch_execz .LBB0_589
	s_ashr_i32 s12, s8, 31
	s_lshr_b32 s12, s12, 29
	s_add_i32 s12, s8, s12
	s_ashr_i32 s13, s12, 3
	s_and_b32 s12, s12, -8
	s_sub_i32 s12, s8, s12
	s_cmp_lt_i32 s12, 0
	s_movk_i32 s14, 0x161
	s_cselect_b32 s14, s14, 0x160
	s_mul_i32 s12, s12, s14
	s_add_i32 s12, s12, s13
	s_mul_hi_i32 s13, s12, 0x2e8ba2e9
	s_lshr_b32 s14, s13, 31
	s_ashr_i32 s13, s13, 4
	s_add_i32 s13, s13, s14
	s_lshl_b32 s14, s13, 2
	s_sub_i32 s15, 0x80, s14
	s_min_i32 s15, s15, 4
	s_abs_i32 s15, s15
	v_cvt_f32_u32_e32 v1, s15
	s_sub_i32 s16, 0, s15
	s_mulk_i32 s13, 0x58
	s_sub_i32 s12, s12, s13
	v_rcp_iflag_f32_e32 v1, v1
	s_ashr_i32 s13, s12, 31
	s_abs_i32 s12, s12
	v_mov_b32_e32 v3, 0
	v_mul_f32_e32 v1, 0x4f7ffffe, v1
	v_cvt_u32_f32_e32 v1, v1
	s_nop 0
	v_readfirstlane_b32 s17, v1
	s_mul_i32 s16, s16, s17
	s_mul_hi_u32 s16, s17, s16
	s_add_i32 s17, s17, s16
	s_mul_hi_u32 s16, s12, s17
	s_mul_i32 s16, s16, s15
	s_sub_i32 s12, s12, s16
	s_sub_i32 s16, s12, s15
	s_cmp_ge_u32 s12, s15
	s_cselect_b32 s12, s16, s12
	s_sub_i32 s16, s12, s15
	s_cmp_ge_u32 s12, s15
	s_cselect_b32 s12, s16, s12
	s_xor_b32 s12, s12, s13
	s_sub_i32 s12, s12, s13
	s_add_i32 s12, s12, s14
	v_lshl_or_b32 v2, s12, 8, v153
	v_lshl_add_u64 v[2:3], v[2:3], 2, s[24:25]
	global_load_dword v111, v[2:3], off
.LBB0_589:
	s_or_b64 exec, exec, s[10:11]
	s_add_u32 s8, s8, s76
	s_addc_u32 s9, s9, s0
	v_mov_b64_e32 v[2:3], 0xaff
	v_cmp_gt_i64_e32 vcc, s[8:9], v[2:3]
	s_cbranch_vccnz .LBB0_598
	s_and_saveexec_b64 s[10:11], s[2:3]
	s_cbranch_execz .LBB0_592
	s_ashr_i32 s12, s8, 31
	s_lshr_b32 s12, s12, 29
	s_add_i32 s12, s8, s12
	s_ashr_i32 s13, s12, 3
	s_and_b32 s12, s12, -8
	s_sub_i32 s12, s8, s12
	s_cmp_lt_i32 s12, 0
	s_movk_i32 s14, 0x161
	s_cselect_b32 s14, s14, 0x160
	s_mul_i32 s12, s12, s14
	s_add_i32 s12, s12, s13
	s_mul_hi_i32 s13, s12, 0x2e8ba2e9
	s_lshr_b32 s14, s13, 31
	s_ashr_i32 s13, s13, 4
	s_add_i32 s13, s13, s14
	s_lshl_b32 s14, s13, 2
	s_sub_i32 s15, 0x80, s14
	s_min_i32 s15, s15, 4
	s_abs_i32 s15, s15
	v_cvt_f32_u32_e32 v1, s15
	s_sub_i32 s16, 0, s15
	s_mulk_i32 s13, 0x58
	s_sub_i32 s12, s12, s13
	v_rcp_iflag_f32_e32 v1, v1
	s_ashr_i32 s13, s12, 31
	s_abs_i32 s12, s12
	v_mov_b32_e32 v3, 0
	v_mul_f32_e32 v1, 0x4f7ffffe, v1
	v_cvt_u32_f32_e32 v1, v1
	s_nop 0
	v_readfirstlane_b32 s17, v1
	s_mul_i32 s16, s16, s17
	s_mul_hi_u32 s16, s17, s16
	s_add_i32 s17, s17, s16
	s_mul_hi_u32 s16, s12, s17
	s_mul_i32 s16, s16, s15
	s_sub_i32 s12, s12, s16
	s_sub_i32 s16, s12, s15
	s_cmp_ge_u32 s12, s15
	s_cselect_b32 s12, s16, s12
	s_sub_i32 s16, s12, s15
	s_cmp_ge_u32 s12, s15
	s_cselect_b32 s12, s16, s12
	s_xor_b32 s12, s12, s13
	s_sub_i32 s12, s12, s13
	s_add_i32 s12, s12, s14
	v_lshl_or_b32 v2, s12, 8, v153
	v_lshl_add_u64 v[2:3], v[2:3], 2, s[24:25]
	global_load_dword v112, v[2:3], off
.LBB0_592:
	s_or_b64 exec, exec, s[10:11]
	s_add_u32 s8, s8, s76
	s_addc_u32 s9, s9, s0
	v_mov_b64_e32 v[2:3], 0xaff
	v_cmp_gt_i64_e32 vcc, s[8:9], v[2:3]
	s_cbranch_vccnz .LBB0_598
	s_and_saveexec_b64 s[10:11], s[2:3]
	s_cbranch_execz .LBB0_595
	s_ashr_i32 s12, s8, 31
	s_lshr_b32 s12, s12, 29
	s_add_i32 s12, s8, s12
	s_ashr_i32 s13, s12, 3
	s_and_b32 s12, s12, -8
	s_sub_i32 s12, s8, s12
	s_cmp_lt_i32 s12, 0
	s_movk_i32 s14, 0x161
	s_cselect_b32 s14, s14, 0x160
	s_mul_i32 s12, s12, s14
	s_add_i32 s12, s12, s13
	s_mul_hi_i32 s13, s12, 0x2e8ba2e9
	s_lshr_b32 s14, s13, 31
	s_ashr_i32 s13, s13, 4
	s_add_i32 s13, s13, s14
	s_lshl_b32 s14, s13, 2
	s_sub_i32 s15, 0x80, s14
	s_min_i32 s15, s15, 4
	s_abs_i32 s15, s15
	v_cvt_f32_u32_e32 v1, s15
	s_sub_i32 s16, 0, s15
	s_mulk_i32 s13, 0x58
	s_sub_i32 s12, s12, s13
	v_rcp_iflag_f32_e32 v1, v1
	s_ashr_i32 s13, s12, 31
	s_abs_i32 s12, s12
	v_mov_b32_e32 v3, 0
	v_mul_f32_e32 v1, 0x4f7ffffe, v1
	v_cvt_u32_f32_e32 v1, v1
	s_nop 0
	v_readfirstlane_b32 s17, v1
	s_mul_i32 s16, s16, s17
	s_mul_hi_u32 s16, s17, s16
	s_add_i32 s17, s17, s16
	s_mul_hi_u32 s16, s12, s17
	s_mul_i32 s16, s16, s15
	s_sub_i32 s12, s12, s16
	s_sub_i32 s16, s12, s15
	s_cmp_ge_u32 s12, s15
	s_cselect_b32 s12, s16, s12
	s_sub_i32 s16, s12, s15
	s_cmp_ge_u32 s12, s15
	s_cselect_b32 s12, s16, s12
	s_xor_b32 s12, s12, s13
	s_sub_i32 s12, s12, s13
	s_add_i32 s12, s12, s14
	v_lshl_or_b32 v2, s12, 8, v153
	v_lshl_add_u64 v[2:3], v[2:3], 2, s[24:25]
	global_load_dword v113, v[2:3], off
.LBB0_595:
	s_or_b64 exec, exec, s[10:11]
	s_add_u32 s8, s8, s76
	s_addc_u32 s9, s9, s0
	v_mov_b64_e32 v[2:3], 0xb00
	v_cmp_lt_i64_e32 vcc, s[8:9], v[2:3]
	s_and_b64 s[10:11], vcc, s[2:3]
	s_and_saveexec_b64 s[2:3], s[10:11]
	s_cbranch_execz .LBB0_597
	s_ashr_i32 s9, s8, 31
	s_lshr_b32 s9, s9, 29
	s_add_i32 s9, s8, s9
	s_ashr_i32 s10, s9, 3
	s_and_b32 s9, s9, -8
	s_sub_i32 s8, s8, s9
	s_cmp_lt_i32 s8, 0
	s_movk_i32 s9, 0x161
	s_cselect_b32 s9, s9, 0x160
	s_mul_i32 s8, s8, s9
	s_add_i32 s8, s8, s10
	s_mul_hi_i32 s9, s8, 0x2e8ba2e9
	s_lshr_b32 s10, s9, 31
	s_ashr_i32 s9, s9, 4
	s_add_i32 s9, s9, s10
	s_lshl_b32 s10, s9, 2
	s_sub_i32 s11, 0x80, s10
	s_min_i32 s11, s11, 4
	s_abs_i32 s11, s11
	v_cvt_f32_u32_e32 v1, s11
	s_sub_i32 s12, 0, s11
	s_mulk_i32 s9, 0x58
	s_sub_i32 s8, s8, s9
	v_rcp_iflag_f32_e32 v1, v1
	s_ashr_i32 s9, s8, 31
	s_abs_i32 s8, s8
	v_mov_b32_e32 v3, 0
	v_mul_f32_e32 v1, 0x4f7ffffe, v1
	v_cvt_u32_f32_e32 v1, v1
	s_nop 0
	v_readfirstlane_b32 s13, v1
	s_mul_i32 s12, s12, s13
	s_mul_hi_u32 s12, s13, s12
	s_add_i32 s13, s13, s12
	s_mul_hi_u32 s12, s8, s13
	s_mul_i32 s12, s12, s11
	s_sub_i32 s8, s8, s12
	s_sub_i32 s12, s8, s11
	s_cmp_ge_u32 s8, s11
	s_cselect_b32 s8, s12, s8
	s_sub_i32 s12, s8, s11
	s_cmp_ge_u32 s8, s11
	s_cselect_b32 s8, s12, s8
	s_xor_b32 s8, s8, s9
	s_sub_i32 s8, s8, s9
	s_add_i32 s8, s8, s10
	v_lshl_or_b32 v2, s8, 8, v153
	v_lshl_add_u64 v[2:3], v[2:3], 2, s[24:25]
	global_load_dword v114, v[2:3], off

; template <class Sched>
; __device__ __forceinline__ void rstd_table(LAS float* rs, const float* ss, const Sched& S) {
;     ...
;     for (int i = 0; i < 15 && S.next(i, u); ++i) if (threadIdx.x < BM) rs[i * BM + threadIdx.x] = rsqrtf(ss[u.pm * BM + threadIdx.x] * (1.0f / DM) + NORM_EPS);
.LBB0_598:
	s_movk_i32 s27, 0x100
	v_cmp_gt_u32_e64 s[38:39], s27, v153
	s_mov_b32 s27, 0x20000
	s_nop 1
	s_and_saveexec_b64 s[50:51], s[38:39]
	v_lshl_add_u32 v115, v153, 2, s27
	s_waitcnt vmcnt(0)
	s_mov_b32 s32, 0x800000
	v_mov_b32_e32 v116, 0x358637bd
	v_fmac_f32_e32 v116, 0x3a800000, v100
	v_mul_f32_e32 v100, 0x4b800000, v116
	v_cmp_gt_f32_e32 vcc, s32, v116
	s_nop 1
	v_cndmask_b32_e32 v100, v116, v100, vcc
	v_rsq_f32_e32 v100, v100
	s_nop 0
	v_mul_f32_e32 v116, 0x45800000, v100
	v_cndmask_b32_e32 v100, v100, v116, vcc
	ds_write_b32 v115, v100
	v_mov_b32_e32 v116, 0x358637bd
	v_fmac_f32_e32 v116, 0x3a800000, v101
	v_mul_f32_e32 v101, 0x4b800000, v116
	v_cmp_gt_f32_e32 vcc, s32, v116
	s_nop 1
	v_cndmask_b32_e32 v101, v116, v101, vcc
	v_rsq_f32_e32 v101, v101
	s_nop 0
	v_mul_f32_e32 v116, 0x45800000, v101
	v_cndmask_b32_e32 v101, v101, v116, vcc
	ds_write_b32 v115, v101 offset:1024
	v_mov_b32_e32 v116, 0x358637bd
	v_fmac_f32_e32 v116, 0x3a800000, v102
	v_mul_f32_e32 v102, 0x4b800000, v116
	v_cmp_gt_f32_e32 vcc, s32, v116
	s_nop 1
	v_cndmask_b32_e32 v102, v116, v102, vcc
	v_rsq_f32_e32 v102, v102
	s_nop 0
	v_mul_f32_e32 v116, 0x45800000, v102
	v_cndmask_b32_e32 v102, v102, v116, vcc
	ds_write_b32 v115, v102 offset:2048
	v_mov_b32_e32 v116, 0x358637bd
	v_fmac_f32_e32 v116, 0x3a800000, v103
	v_mul_f32_e32 v103, 0x4b800000, v116
	v_cmp_gt_f32_e32 vcc, s32, v116
	s_nop 1
	v_cndmask_b32_e32 v103, v116, v103, vcc
	v_rsq_f32_e32 v103, v103
	s_nop 0
	v_mul_f32_e32 v116, 0x45800000, v103
	v_cndmask_b32_e32 v103, v103, v116, vcc
	ds_write_b32 v115, v103 offset:3072
	v_mov_b32_e32 v116, 0x358637bd
	v_fmac_f32_e32 v116, 0x3a800000, v104
	v_mul_f32_e32 v104, 0x4b800000, v116
	v_cmp_gt_f32_e32 vcc, s32, v116
	s_nop 1
	v_cndmask_b32_e32 v104, v116, v104, vcc
	v_rsq_f32_e32 v104, v104
	s_nop 0
	v_mul_f32_e32 v116, 0x45800000, v104
	v_cndmask_b32_e32 v104, v104, v116, vcc
	ds_write_b32 v115, v104 offset:4096
	v_mov_b32_e32 v116, 0x358637bd
	v_fmac_f32_e32 v116, 0x3a800000, v105
	v_mul_f32_e32 v105, 0x4b800000, v116
	v_cmp_gt_f32_e32 vcc, s32, v116
	s_nop 1
	v_cndmask_b32_e32 v105, v116, v105, vcc
	v_rsq_f32_e32 v105, v105
	s_nop 0
	v_mul_f32_e32 v116, 0x45800000, v105
	v_cndmask_b32_e32 v105, v105, v116, vcc
	ds_write_b32 v115, v105 offset:5120
	v_mov_b32_e32 v116, 0x358637bd
	v_fmac_f32_e32 v116, 0x3a800000, v106
	v_mul_f32_e32 v106, 0x4b800000, v116
	v_cmp_gt_f32_e32 vcc, s32, v116
	s_nop 1
	v_cndmask_b32_e32 v106, v116, v106, vcc
	v_rsq_f32_e32 v106, v106
	s_nop 0
	v_mul_f32_e32 v116, 0x45800000, v106
	v_cndmask_b32_e32 v106, v106, v116, vcc
	ds_write_b32 v115, v106 offset:6144
	v_mov_b32_e32 v116, 0x358637bd
	v_fmac_f32_e32 v116, 0x3a800000, v107
	v_mul_f32_e32 v107, 0x4b800000, v116
	v_cmp_gt_f32_e32 vcc, s32, v116
	s_nop 1
	v_cndmask_b32_e32 v107, v116, v107, vcc
	v_rsq_f32_e32 v107, v107
	s_nop 0
	v_mul_f32_e32 v116, 0x45800000, v107
	v_cndmask_b32_e32 v107, v107, v116, vcc
	ds_write_b32 v115, v107 offset:7168
	v_mov_b32_e32 v116, 0x358637bd
	v_fmac_f32_e32 v116, 0x3a800000, v108
	v_mul_f32_e32 v108, 0x4b800000, v116
	v_cmp_gt_f32_e32 vcc, s32, v116
	s_nop 1
	v_cndmask_b32_e32 v108, v116, v108, vcc
	v_rsq_f32_e32 v108, v108
	s_nop 0
	v_mul_f32_e32 v116, 0x45800000, v108
	v_cndmask_b32_e32 v108, v108, v116, vcc
	ds_write_b32 v115, v108 offset:8192
	v_mov_b32_e32 v116, 0x358637bd
	v_fmac_f32_e32 v116, 0x3a800000, v109
	v_mul_f32_e32 v109, 0x4b800000, v116
	v_cmp_gt_f32_e32 vcc, s32, v116
	s_nop 1
	v_cndmask_b32_e32 v109, v116, v109, vcc
	v_rsq_f32_e32 v109, v109
	s_nop 0
	v_mul_f32_e32 v116, 0x45800000, v109
	v_cndmask_b32_e32 v109, v109, v116, vcc
	ds_write_b32 v115, v109 offset:9216
	v_mov_b32_e32 v116, 0x358637bd
	v_fmac_f32_e32 v116, 0x3a800000, v110
	v_mul_f32_e32 v110, 0x4b800000, v116
	v_cmp_gt_f32_e32 vcc, s32, v116
	s_nop 1
	v_cndmask_b32_e32 v110, v116, v110, vcc
	v_rsq_f32_e32 v110, v110
	s_nop 0
	v_mul_f32_e32 v116, 0x45800000, v110
	v_cndmask_b32_e32 v110, v110, v116, vcc
	ds_write_b32 v115, v110 offset:10240
	v_mov_b32_e32 v116, 0x358637bd
	v_fmac_f32_e32 v116, 0x3a800000, v111
	v_mul_f32_e32 v111, 0x4b800000, v116
	v_cmp_gt_f32_e32 vcc, s32, v116
	s_nop 1
	v_cndmask_b32_e32 v111, v116, v111, vcc
	v_rsq_f32_e32 v111, v111
	s_nop 0
	v_mul_f32_e32 v116, 0x45800000, v111
	v_cndmask_b32_e32 v111, v111, v116, vcc
	ds_write_b32 v115, v111 offset:11264
	v_mov_b32_e32 v116, 0x358637bd
	v_fmac_f32_e32 v116, 0x3a800000, v112
	v_mul_f32_e32 v112, 0x4b800000, v116
	v_cmp_gt_f32_e32 vcc, s32, v116
	s_nop 1
	v_cndmask_b32_e32 v112, v116, v112, vcc
	v_rsq_f32_e32 v112, v112
	s_nop 0
	v_mul_f32_e32 v116, 0x45800000, v112
	v_cndmask_b32_e32 v112, v112, v116, vcc
	ds_write_b32 v115, v112 offset:12288
	v_mov_b32_e32 v116, 0x358637bd
	v_fmac_f32_e32 v116, 0x3a800000, v113
	v_mul_f32_e32 v113, 0x4b800000, v116
	v_cmp_gt_f32_e32 vcc, s32, v116
	s_nop 1
	v_cndmask_b32_e32 v113, v116, v113, vcc
	v_rsq_f32_e32 v113, v113
	s_nop 0
	v_mul_f32_e32 v116, 0x45800000, v113
	v_cndmask_b32_e32 v113, v113, v116, vcc
	ds_write_b32 v115, v113 offset:13312
	v_mov_b32_e32 v116, 0x358637bd
	v_fmac_f32_e32 v116, 0x3a800000, v114
	v_mul_f32_e32 v114, 0x4b800000, v116
	v_cmp_gt_f32_e32 vcc, s32, v116
	s_nop 1
	v_cndmask_b32_e32 v114, v116, v114, vcc
	v_rsq_f32_e32 v114, v114
	s_nop 0
	v_mul_f32_e32 v116, 0x45800000, v114
	v_cndmask_b32_e32 v114, v114, v116, vcc
	ds_write_b32 v115, v114 offset:14336
	s_or_b64 exec, exec, s[50:51]
	s_andn2_b64 vcc, exec, s[6:7]
	v_readfirstlane_b32 s3, v153
	s_cbranch_vccnz .LBB0_614
; #define PG8_STAGE(bufoff, gbase, voff) do { _Pragma("unroll") for (int _i = 0; _i < 2; ++_i) \
;         __builtin_amdgcn_global_load_lds((const unsigned*)((const char*)(gbase) + (voff)[_i]), (LAS unsigned*)(lds + (bufoff) + ldsw + _i * 8192), 16, 0, 0); } while (0)
; #define PG8_WAIT_V(n) asm volatile("s_waitcnt vmcnt(" #n ")" ::: "memory")
; #define PG8_BAR __builtin_amdgcn_s_barrier()
; template <class Epi, class Sched, bool ALIGN_EPI>
; __device__ __forceinline__ void gemm_phase(LAS unsigned char* lds, const Gemm g, const Sched& S, const Epi& E) {
;     const int tid = threadIdx.x, wid = __builtin_amdgcn_readfirstlane(tid >> 6), lane = tid & 63, wr = wid >> 2, wc = wid & 3, fr = lane & 15, fq = lane >> 4;
;     const int K = g.K, nt = K / BK;
;     unsigned voffA[2], voffB[2];
; #pragma unroll
;     for (int i = 0; i < 2; ++i) { int R, C; stage_rc(tid * 16 + i * 8192, R, C); const int Rb = (R & ~31) + perm32(R & 31);
;         voffA[i] = (unsigned)(R * g.lda + C) * 2u; voffB[i] = (unsigned)(Rb * g.ldb + C) * 2u; }
;     const size_t kstep = (size_t)(BK * 2);
;     const size_t hstepA = (size_t)HALF * g.lda * 2, hstepB = (size_t)HALF * g.ldb * 2;
;     const size_t tstepA = 2 * hstepA, tstepB = 2 * hstepB;
;     const unsigned ldsw = (unsigned)wid * 1024u;
;     const int aoff = lds_byte(wr * 64 + fr, fq * 8), boff = lds_byte(wc * 32 + fr, fq * 8);
;     ...
;     Unit cur, nxt; int ui = 0;
;     if (!S.next(0, cur)) return;
;     Acc acc;
; #pragma unroll
;     for (int a = 0; a < 2; ++a)
; #pragma unroll
;         for (int b = 0; b < 2; ++b)
; #pragma unroll
;             for (int m = 0; m < 4; ++m)
; #pragma unroll
;                 for (int n = 0; n < 2; ++n) acc[a][b][m][n] = (f32x4){0.f, 0.f, 0.f, 0.f};
;     bf16x8 At[4][2], B0[2][2], B1[2][2];
;     const char* cA = (const char*)g.A + (size_t)cur.pm * tstepA; const char* cB = (const char*)g.Bt + (size_t)cur.pn * tstepB;
;     PG8_STAGE(PG8_SB(0, 0), cB, voffB); PG8_STAGE(PG8_SB(0, 1), cB + hstepB, voffB); PG8_STAGE(PG8_SA(0, 0), cA, voffA); PG8_STAGE(PG8_SA(0, 1), cA + hstepA, voffA);
;     if (wr == 1) PG8_BAR;
;     PG8_WAIT_V(2); PG8_BAR;
;     PG8_STAGE(PG8_SB(1, 0), cB + kstep, voffB); PG8_STAGE(PG8_SA(1, 0), cA + kstep, voffA); PG8_STAGE(PG8_SB(1, 1), cB + hstepB + kstep, voffB);
;     PG8_WAIT_V(6); PG8_BAR;
	s_waitcnt vmcnt(4)
	v_lshrrev_b32_e32 v0, 5, v153
	v_lshrrev_b32_e32 v2, 1, v153
	v_and_b32_e32 v0, 4, v0
	v_bfe_u32 v1, v153, 2, 2
	v_and_b32_e32 v11, 24, v2
	v_or3_b32 v0, v0, v1, v11
	v_lshlrev_b32_e32 v1, 4, v153
	v_add_u32_e32 v8, 0x2000, v1
	s_lshr_b32 s8, s3, 6
	v_lshrrev_b32_e32 v2, 7, v8
	s_movk_i32 s2, 0xe0
	v_and_b32_e32 v4, 32, v153
	s_lshr_b32 s10, s3, 8
	s_lshl_b32 s28, s8, 10
	v_and_or_b32 v3, v2, s2, v0
	v_bitop3_b32 v9, v1, v4, 48 bitop3:0x6c
	v_and_b32_e32 v10, 64, v153
	v_bfe_u32 v12, v153, 2, 4
	s_movk_i32 s2, 0xf0
	s_add_u32 s29, s74, 0x3800000
	v_or_b32_e32 v1, v9, v10
	v_and_or_b32 v2, v2, s2, v12
	s_addc_u32 s30, s75, 0
	v_lshl_or_b32 v130, v2, 11, v1
	v_lshrrev_b32_e32 v2, 3, v153
	s_movk_i32 s2, 0x60
	s_add_u32 s31, s74, 0x100000
	v_and_or_b32 v0, v2, s2, v0
	s_movk_i32 s2, 0x70
	s_addc_u32 s33, s75, 0
	v_lshl_or_b32 v132, v0, 11, v1
	v_and_or_b32 v0, v2, s2, v12
	s_lshr_b32 s2, s1, 29
	s_add_i32 s2, s97, s2
	s_ashr_i32 s6, s2, 3
	s_and_b32 s2, s2, -8
	s_sub_i32 s2, s97, s2
	s_cmp_lt_i32 s2, 0
	s_movk_i32 s34, 0x161
	s_cselect_b32 s7, s34, 0x160
	s_mul_i32 s2, s2, s7
	s_add_i32 s2, s2, s6
	s_mul_hi_i32 s6, s2, 0x2e8ba2e9
	s_lshr_b32 s7, s6, 31
	s_ashr_i32 s6, s6, 4
	s_add_i32 s6, s6, s7
	s_lshl_b32 s7, s6, 2
	s_mulk_i32 s6, 0x58
	s_sub_i32 s6, s2, s6
	s_bfe_i32 s2, s6, 0x80000
	s_bfe_u32 s2, s2, 0x2000d
	s_add_i32 s9, s6, s2
	s_bfe_i32 s2, s9, 0x80000
	s_and_b32 s9, s9, 0xfc
	s_sub_i32 s6, s6, s9
	s_sext_i32_i16 s2, s2
	s_sext_i32_i8 s6, s6
	s_lshr_b32 s2, s2, 2
	s_add_i32 s20, s7, s6
	s_ashr_i32 s21, s20, 31
	s_bfe_i64 s[12:13], s[2:3], 0x100000
	s_lshl_b64 s[6:7], s[20:21], 19
	s_lshl_b64 s[12:13], s[12:13], 19
	s_add_u32 s24, s31, s12
	s_addc_u32 s25, s33, s13
	s_add_i32 s21, s28, 0
	s_add_i32 m0, s21, 0x10000
	v_lshl_or_b32 v128, v3, 11, v1
	global_load_lds_dwordx4 v132, s[24:25]
	s_add_i32 m0, s21, 0x12000
	s_add_u32 s12, s24, 0x40000
	global_load_lds_dwordx4 v128, s[24:25]
	s_addc_u32 s13, s25, 0
	s_add_i32 m0, s21, 0x14000
	v_lshl_or_b32 v134, v0, 11, v1
	global_load_lds_dwordx4 v132, s[12:13]
	s_add_i32 m0, s21, 0x16000
	s_add_u32 s22, s29, s6
	s_addc_u32 s23, s30, s7
	s_add_i32 s35, s21, 0x2000
	global_load_lds_dwordx4 v128, s[12:13]
	s_mov_b32 m0, s21
	s_add_u32 s6, s22, 0x40000
	global_load_lds_dwordx4 v134, s[22:23]
	s_mov_b32 m0, s35
	s_addc_u32 s7, s23, 0
	s_add_i32 s36, s21, 0x4000
	global_load_lds_dwordx4 v130, s[22:23]
	s_mov_b32 m0, s36
	s_add_i32 s37, s21, 0x6000
	global_load_lds_dwordx4 v134, s[6:7]
	s_mov_b32 m0, s37
	v_mov_b32_e32 v133, 0
	global_load_lds_dwordx4 v130, s[6:7]
	v_mov_b32_e32 v129, v133
	v_mov_b32_e32 v135, v133
	v_mov_b32_e32 v131, v133
	s_cmp_eq_u32 s10, 1
	s_mov_b32 s45, 0
	v_lshl_add_u64 v[6:7], s[24:25], 0, v[132:133]
	v_lshl_add_u64 v[4:5], s[24:25], 0, v[128:129]
	v_lshl_add_u64 v[0:1], s[22:23], 0, v[134:135]
	s_cselect_b64 s[6:7], -1, 0
	s_cmp_lg_u32 s10, 1
	v_lshl_add_u64 v[2:3], s[22:23], 0, v[130:131]
	s_cbranch_scc1 .LBB0_601
	s_barrier

; #define LAS __attribute__((address_space(3)))
;     __host__ __device__ bool next(int i, Unit& u) const {
;         const long L = (long)i * G + c; if (L >= nwg) return false;
;         int wgid = (int)L; { const int q = nwg / NXCD, r = nwg % NXCD, xcd = wgid % NXCD, off = wgid / NXCD; wgid = (xcd < r ? xcd * (q + 1) : r * (q + 1) + (xcd - r) * q) + off; }
;         const int nig = WGM * nN, gid = wgid / nig, fm = gid * WGM, gsz = (nM - fm) < WGM ? (nM - fm) : WGM;
;         u.pm = fm + ((wgid % nig) % gsz); u.pn = (wgid % nig) / gsz; u.idx = i; return true;
; template <class Sched>
; __device__ __forceinline__ void rstd_table(LAS float* rs, const float* ss, const Sched& S) {
;     Unit u;
;     for (int i = 0; i < 15 && S.next(i, u); ++i) if (threadIdx.x < BM) rs[i * BM + threadIdx.x] = rsqrtf(ss[u.pm * BM + threadIdx.x] * (1.0f / DM) + NORM_EPS);
; }
.LBB0_817:
	s_cmp_lt_i32 s88, 4
	s_cselect_b64 s[0:1], -1, 0
	s_cmp_gt_i32 s89, 3
	s_cselect_b64 s[2:3], -1, 0
	s_and_b64 s[0:1], s[0:1], s[2:3]
	s_andn2_b64 vcc, exec, s[0:1]
	s_waitcnt lgkmcnt(0)
	s_cbranch_vccnz .LBB0_961
	s_ashr_i32 s0, s76, 31
	s_ashr_i32 s1, s97, 31
	s_cmpk_lt_i32 s97, 0x900
	s_cselect_b64 s[4:5], -1, 0
	s_cmpk_gt_i32 s97, 0x8ff
	s_cbranch_scc1 .LBB0_863
	s_movk_i32 s2, 0x100
	s_add_i32 s6, 0, 0x20000
	v_cmp_gt_u32_e64 s[2:3], s2, v153
	s_waitcnt vmcnt(0)
	v_lshl_add_u32 v0, v153, 2, s6
	s_and_saveexec_b64 s[6:7], s[2:3]
	s_cbranch_execz .LBB0_821
	s_lshr_b32 s10, s1, 29
	s_add_i32 s10, s97, s10
	s_and_b32 s11, s10, -8
	s_sub_i32 s11, s97, s11
	s_cmp_lt_i32 s11, 0
	s_movk_i32 s12, 0x121
	s_cselect_b32 s12, s12, 0x120
	s_mul_i32 s11, s11, s12
	s_ashr_i32 s10, s10, 3
	s_add_i32 s11, s11, s10
	s_mul_hi_i32 s10, s11, 0x38e38e39
	s_lshr_b32 s12, s10, 31
	s_ashr_i32 s10, s10, 4
	s_add_i32 s10, s10, s12
	s_lshl_b32 s12, s10, 2
	s_sub_i32 s13, 0x80, s12
	s_min_i32 s13, s13, 4
	s_abs_i32 s13, s13
	v_cvt_f32_u32_e32 v1, s13
	s_sub_i32 s14, 0, s13
	s_mulk_i32 s10, 0x48
	s_sub_i32 s10, s11, s10
	v_rcp_iflag_f32_e32 v1, v1
	s_ashr_i32 s11, s10, 31
	s_abs_i32 s10, s10
	v_mov_b32_e32 v3, 0
	v_mul_f32_e32 v1, 0x4f7ffffe, v1
	v_cvt_u32_f32_e32 v1, v1
	s_nop 0
	v_readfirstlane_b32 s15, v1
	s_mul_i32 s14, s14, s15
	s_mul_hi_u32 s14, s15, s14
	s_add_i32 s15, s15, s14
	s_mul_hi_u32 s14, s10, s15
	s_mul_i32 s14, s14, s13
	s_sub_i32 s10, s10, s14
	s_sub_i32 s14, s10, s13
	s_cmp_ge_u32 s10, s13
	s_cselect_b32 s10, s14, s10
	s_sub_i32 s14, s10, s13
	s_cmp_ge_u32 s10, s13
	s_cselect_b32 s10, s14, s10
	s_xor_b32 s10, s10, s11
	s_sub_i32 s10, s10, s11
	s_add_i32 s10, s10, s12
	v_lshl_or_b32 v2, s10, 8, v153
	v_lshl_add_u64 v[2:3], v[2:3], 2, s[8:9]
	global_load_dword v100, v[2:3], off
.LBB0_821:
	s_or_b64 exec, exec, s[6:7]
	s_add_u32 s6, s76, s97
	s_addc_u32 s7, s0, s1
	v_mov_b64_e32 v[2:3], 0x8ff
	v_cmp_gt_i64_e32 vcc, s[6:7], v[2:3]
	s_cbranch_vccnz .LBB0_863
	s_and_saveexec_b64 s[10:11], s[2:3]
	s_cbranch_execz .LBB0_824
	s_ashr_i32 s12, s6, 31
	s_lshr_b32 s12, s12, 29
	s_add_i32 s12, s6, s12
	s_ashr_i32 s13, s12, 3
	s_and_b32 s12, s12, -8
	s_sub_i32 s12, s6, s12
	s_cmp_lt_i32 s12, 0
	s_movk_i32 s14, 0x121
	s_cselect_b32 s14, s14, 0x120
	s_mul_i32 s12, s12, s14
	s_add_i32 s12, s12, s13
	s_mul_hi_i32 s13, s12, 0x38e38e39
	s_lshr_b32 s14, s13, 31
	s_ashr_i32 s13, s13, 4
	s_add_i32 s13, s13, s14
	s_lshl_b32 s14, s13, 2
	s_sub_i32 s15, 0x80, s14
	s_min_i32 s15, s15, 4
	s_abs_i32 s15, s15
	v_cvt_f32_u32_e32 v1, s15
	s_sub_i32 s16, 0, s15
	s_mulk_i32 s13, 0x48
	s_sub_i32 s12, s12, s13
	v_rcp_iflag_f32_e32 v1, v1
	s_ashr_i32 s13, s12, 31
	s_abs_i32 s12, s12
	v_mov_b32_e32 v3, 0
	v_mul_f32_e32 v1, 0x4f7ffffe, v1
	v_cvt_u32_f32_e32 v1, v1
	s_nop 0
	v_readfirstlane_b32 s17, v1
	s_mul_i32 s16, s16, s17
	s_mul_hi_u32 s16, s17, s16
	s_add_i32 s17, s17, s16
	s_mul_hi_u32 s16, s12, s17
	s_mul_i32 s16, s16, s15
	s_sub_i32 s12, s12, s16
	s_sub_i32 s16, s12, s15
	s_cmp_ge_u32 s12, s15
	s_cselect_b32 s12, s16, s12
	s_sub_i32 s16, s12, s15
	s_cmp_ge_u32 s12, s15
	s_cselect_b32 s12, s16, s12
	s_xor_b32 s12, s12, s13
	s_sub_i32 s12, s12, s13
	s_add_i32 s12, s12, s14
	v_lshl_or_b32 v2, s12, 8, v153
	v_lshl_add_u64 v[2:3], v[2:3], 2, s[8:9]
	global_load_dword v101, v[2:3], off
.LBB0_824:
	s_or_b64 exec, exec, s[10:11]
	s_add_u32 s6, s6, s76
	s_addc_u32 s7, s7, s0
	v_mov_b64_e32 v[2:3], 0x8ff
	v_cmp_gt_i64_e32 vcc, s[6:7], v[2:3]
	s_cbranch_vccnz .LBB0_863
	s_and_saveexec_b64 s[10:11], s[2:3]
	s_cbranch_execz .LBB0_827
	s_ashr_i32 s12, s6, 31
	s_lshr_b32 s12, s12, 29
	s_add_i32 s12, s6, s12
	s_ashr_i32 s13, s12, 3
	s_and_b32 s12, s12, -8
	s_sub_i32 s12, s6, s12
	s_cmp_lt_i32 s12, 0
	s_movk_i32 s14, 0x121
	s_cselect_b32 s14, s14, 0x120
	s_mul_i32 s12, s12, s14
	s_add_i32 s12, s12, s13
	s_mul_hi_i32 s13, s12, 0x38e38e39
	s_lshr_b32 s14, s13, 31
	s_ashr_i32 s13, s13, 4
	s_add_i32 s13, s13, s14
	s_lshl_b32 s14, s13, 2
	s_sub_i32 s15, 0x80, s14
	s_min_i32 s15, s15, 4
	s_abs_i32 s15, s15
	v_cvt_f32_u32_e32 v1, s15
	s_sub_i32 s16, 0, s15
	s_mulk_i32 s13, 0x48
	s_sub_i32 s12, s12, s13
	v_rcp_iflag_f32_e32 v1, v1
	s_ashr_i32 s13, s12, 31
	s_abs_i32 s12, s12
	v_mov_b32_e32 v3, 0
	v_mul_f32_e32 v1, 0x4f7ffffe, v1
	v_cvt_u32_f32_e32 v1, v1
	s_nop 0
	v_readfirstlane_b32 s17, v1
	s_mul_i32 s16, s16, s17
	s_mul_hi_u32 s16, s17, s16
	s_add_i32 s17, s17, s16
	s_mul_hi_u32 s16, s12, s17
	s_mul_i32 s16, s16, s15
	s_sub_i32 s12, s12, s16
	s_sub_i32 s16, s12, s15
	s_cmp_ge_u32 s12, s15
	s_cselect_b32 s12, s16, s12
	s_sub_i32 s16, s12, s15
	s_cmp_ge_u32 s12, s15
	s_cselect_b32 s12, s16, s12
	s_xor_b32 s12, s12, s13
	s_sub_i32 s12, s12, s13
	s_add_i32 s12, s12, s14
	v_lshl_or_b32 v2, s12, 8, v153
	v_lshl_add_u64 v[2:3], v[2:3], 2, s[8:9]
	global_load_dword v102, v[2:3], off
.LBB0_827:
	s_or_b64 exec, exec, s[10:11]
	s_add_u32 s6, s6, s76
	s_addc_u32 s7, s7, s0
	v_mov_b64_e32 v[2:3], 0x8ff
	v_cmp_gt_i64_e32 vcc, s[6:7], v[2:3]
	s_cbranch_vccnz .LBB0_863
	s_and_saveexec_b64 s[10:11], s[2:3]
	s_cbranch_execz .LBB0_830
	s_ashr_i32 s12, s6, 31
	s_lshr_b32 s12, s12, 29
	s_add_i32 s12, s6, s12
	s_ashr_i32 s13, s12, 3
	s_and_b32 s12, s12, -8
	s_sub_i32 s12, s6, s12
	s_cmp_lt_i32 s12, 0
	s_movk_i32 s14, 0x121
	s_cselect_b32 s14, s14, 0x120
	s_mul_i32 s12, s12, s14
	s_add_i32 s12, s12, s13
	s_mul_hi_i32 s13, s12, 0x38e38e39
	s_lshr_b32 s14, s13, 31
	s_ashr_i32 s13, s13, 4
	s_add_i32 s13, s13, s14
	s_lshl_b32 s14, s13, 2
	s_sub_i32 s15, 0x80, s14
	s_min_i32 s15, s15, 4
	s_abs_i32 s15, s15
	v_cvt_f32_u32_e32 v1, s15
	s_sub_i32 s16, 0, s15
	s_mulk_i32 s13, 0x48
	s_sub_i32 s12, s12, s13
	v_rcp_iflag_f32_e32 v1, v1
	s_ashr_i32 s13, s12, 31
	s_abs_i32 s12, s12
	v_mov_b32_e32 v3, 0
	v_mul_f32_e32 v1, 0x4f7ffffe, v1
	v_cvt_u32_f32_e32 v1, v1
	s_nop 0
	v_readfirstlane_b32 s17, v1
	s_mul_i32 s16, s16, s17
	s_mul_hi_u32 s16, s17, s16
	s_add_i32 s17, s17, s16
	s_mul_hi_u32 s16, s12, s17
	s_mul_i32 s16, s16, s15
	s_sub_i32 s12, s12, s16
	s_sub_i32 s16, s12, s15
	s_cmp_ge_u32 s12, s15
	s_cselect_b32 s12, s16, s12
	s_sub_i32 s16, s12, s15
	s_cmp_ge_u32 s12, s15
	s_cselect_b32 s12, s16, s12
	s_xor_b32 s12, s12, s13
	s_sub_i32 s12, s12, s13
	s_add_i32 s12, s12, s14
	v_lshl_or_b32 v2, s12, 8, v153
	v_lshl_add_u64 v[2:3], v[2:3], 2, s[8:9]
	global_load_dword v103, v[2:3], off
; #define LAS __attribute__((address_space(3)))
;     __host__ __device__ bool next(int i, Unit& u) const {
;         const long L = (long)i * G + c; if (L >= nwg) return false;
;         int wgid = (int)L; { const int q = nwg / NXCD, r = nwg % NXCD, xcd = wgid % NXCD, off = wgid / NXCD; wgid = (xcd < r ? xcd * (q + 1) : r * (q + 1) + (xcd - r) * q) + off; }
;         const int nig = WGM * nN, gid = wgid / nig, fm = gid * WGM, gsz = (nM - fm) < WGM ? (nM - fm) : WGM;
;         u.pm = fm + ((wgid % nig) % gsz); u.pn = (wgid % nig) / gsz; u.idx = i; return true;
; template <class Sched>
; __device__ __forceinline__ void rstd_table(LAS float* rs, const float* ss, const Sched& S) {
;     Unit u;
;     for (int i = 0; i < 15 && S.next(i, u); ++i) if (threadIdx.x < BM) rs[i * BM + threadIdx.x] = rsqrtf(ss[u.pm * BM + threadIdx.x] * (1.0f / DM) + NORM_EPS);
; }
.LBB0_830:
	s_or_b64 exec, exec, s[10:11]
	s_add_u32 s6, s6, s76
	s_addc_u32 s7, s7, s0
	v_mov_b64_e32 v[2:3], 0x8ff
	v_cmp_gt_i64_e32 vcc, s[6:7], v[2:3]
	s_cbranch_vccnz .LBB0_863
	s_and_saveexec_b64 s[10:11], s[2:3]
	s_cbranch_execz .LBB0_833
	s_ashr_i32 s12, s6, 31
	s_lshr_b32 s12, s12, 29
	s_add_i32 s12, s6, s12
	s_ashr_i32 s13, s12, 3
	s_and_b32 s12, s12, -8
	s_sub_i32 s12, s6, s12
	s_cmp_lt_i32 s12, 0
	s_movk_i32 s14, 0x121
	s_cselect_b32 s14, s14, 0x120
	s_mul_i32 s12, s12, s14
	s_add_i32 s12, s12, s13
	s_mul_hi_i32 s13, s12, 0x38e38e39
	s_lshr_b32 s14, s13, 31
	s_ashr_i32 s13, s13, 4
	s_add_i32 s13, s13, s14
	s_lshl_b32 s14, s13, 2
	s_sub_i32 s15, 0x80, s14
	s_min_i32 s15, s15, 4
	s_abs_i32 s15, s15
	v_cvt_f32_u32_e32 v1, s15
	s_sub_i32 s16, 0, s15
	s_mulk_i32 s13, 0x48
	s_sub_i32 s12, s12, s13
	v_rcp_iflag_f32_e32 v1, v1
	s_ashr_i32 s13, s12, 31
	s_abs_i32 s12, s12
	v_mov_b32_e32 v3, 0
	v_mul_f32_e32 v1, 0x4f7ffffe, v1
	v_cvt_u32_f32_e32 v1, v1
	s_nop 0
	v_readfirstlane_b32 s17, v1
	s_mul_i32 s16, s16, s17
	s_mul_hi_u32 s16, s17, s16
	s_add_i32 s17, s17, s16
	s_mul_hi_u32 s16, s12, s17
	s_mul_i32 s16, s16, s15
	s_sub_i32 s12, s12, s16
	s_sub_i32 s16, s12, s15
	s_cmp_ge_u32 s12, s15
	s_cselect_b32 s12, s16, s12
	s_sub_i32 s16, s12, s15
	s_cmp_ge_u32 s12, s15
	s_cselect_b32 s12, s16, s12
	s_xor_b32 s12, s12, s13
	s_sub_i32 s12, s12, s13
	s_add_i32 s12, s12, s14
	v_lshl_or_b32 v2, s12, 8, v153
	v_lshl_add_u64 v[2:3], v[2:3], 2, s[8:9]
	global_load_dword v104, v[2:3], off
.LBB0_833:
	s_or_b64 exec, exec, s[10:11]
	s_add_u32 s6, s6, s76
	s_addc_u32 s7, s7, s0
	v_mov_b64_e32 v[2:3], 0x8ff
	v_cmp_gt_i64_e32 vcc, s[6:7], v[2:3]
	s_cbranch_vccnz .LBB0_863
	s_and_saveexec_b64 s[10:11], s[2:3]
	s_cbranch_execz .LBB0_836
	s_ashr_i32 s12, s6, 31
	s_lshr_b32 s12, s12, 29
	s_add_i32 s12, s6, s12
	s_ashr_i32 s13, s12, 3
	s_and_b32 s12, s12, -8
	s_sub_i32 s12, s6, s12
	s_cmp_lt_i32 s12, 0
	s_movk_i32 s14, 0x121
	s_cselect_b32 s14, s14, 0x120
	s_mul_i32 s12, s12, s14
	s_add_i32 s12, s12, s13
	s_mul_hi_i32 s13, s12, 0x38e38e39
	s_lshr_b32 s14, s13, 31
	s_ashr_i32 s13, s13, 4
	s_add_i32 s13, s13, s14
	s_lshl_b32 s14, s13, 2
	s_sub_i32 s15, 0x80, s14
	s_min_i32 s15, s15, 4
	s_abs_i32 s15, s15
	v_cvt_f32_u32_e32 v1, s15
	s_sub_i32 s16, 0, s15
	s_mulk_i32 s13, 0x48
	s_sub_i32 s12, s12, s13
	v_rcp_iflag_f32_e32 v1, v1
	s_ashr_i32 s13, s12, 31
	s_abs_i32 s12, s12
	v_mov_b32_e32 v3, 0
	v_mul_f32_e32 v1, 0x4f7ffffe, v1
	v_cvt_u32_f32_e32 v1, v1
	s_nop 0
	v_readfirstlane_b32 s17, v1
	s_mul_i32 s16, s16, s17
	s_mul_hi_u32 s16, s17, s16
	s_add_i32 s17, s17, s16
	s_mul_hi_u32 s16, s12, s17
	s_mul_i32 s16, s16, s15
	s_sub_i32 s12, s12, s16
	s_sub_i32 s16, s12, s15
	s_cmp_ge_u32 s12, s15
	s_cselect_b32 s12, s16, s12
	s_sub_i32 s16, s12, s15
	s_cmp_ge_u32 s12, s15
	s_cselect_b32 s12, s16, s12
	s_xor_b32 s12, s12, s13
	s_sub_i32 s12, s12, s13
	s_add_i32 s12, s12, s14
	v_lshl_or_b32 v2, s12, 8, v153
	v_lshl_add_u64 v[2:3], v[2:3], 2, s[8:9]
	global_load_dword v105, v[2:3], off
.LBB0_836:
	s_or_b64 exec, exec, s[10:11]
	s_add_u32 s6, s6, s76
	s_addc_u32 s7, s7, s0
	v_mov_b64_e32 v[2:3], 0x8ff
	v_cmp_gt_i64_e32 vcc, s[6:7], v[2:3]
	s_cbranch_vccnz .LBB0_863
	s_and_saveexec_b64 s[10:11], s[2:3]
	s_cbranch_execz .LBB0_839
	s_ashr_i32 s12, s6, 31
	s_lshr_b32 s12, s12, 29
	s_add_i32 s12, s6, s12
	s_ashr_i32 s13, s12, 3
	s_and_b32 s12, s12, -8
	s_sub_i32 s12, s6, s12
	s_cmp_lt_i32 s12, 0
	s_movk_i32 s14, 0x121
	s_cselect_b32 s14, s14, 0x120
	s_mul_i32 s12, s12, s14
	s_add_i32 s12, s12, s13
	s_mul_hi_i32 s13, s12, 0x38e38e39
	s_lshr_b32 s14, s13, 31
	s_ashr_i32 s13, s13, 4
	s_add_i32 s13, s13, s14
	s_lshl_b32 s14, s13, 2
	s_sub_i32 s15, 0x80, s14
	s_min_i32 s15, s15, 4
	s_abs_i32 s15, s15
	v_cvt_f32_u32_e32 v1, s15
	s_sub_i32 s16, 0, s15
	s_mulk_i32 s13, 0x48
	s_sub_i32 s12, s12, s13
	v_rcp_iflag_f32_e32 v1, v1
	s_ashr_i32 s13, s12, 31
	s_abs_i32 s12, s12
	v_mov_b32_e32 v3, 0
	v_mul_f32_e32 v1, 0x4f7ffffe, v1
	v_cvt_u32_f32_e32 v1, v1
	s_nop 0
	v_readfirstlane_b32 s17, v1
	s_mul_i32 s16, s16, s17
	s_mul_hi_u32 s16, s17, s16
	s_add_i32 s17, s17, s16
	s_mul_hi_u32 s16, s12, s17
	s_mul_i32 s16, s16, s15
	s_sub_i32 s12, s12, s16
	s_sub_i32 s16, s12, s15
	s_cmp_ge_u32 s12, s15
	s_cselect_b32 s12, s16, s12
	s_sub_i32 s16, s12, s15
	s_cmp_ge_u32 s12, s15
	s_cselect_b32 s12, s16, s12
	s_xor_b32 s12, s12, s13
	s_sub_i32 s12, s12, s13
	s_add_i32 s12, s12, s14
	v_lshl_or_b32 v2, s12, 8, v153
	v_lshl_add_u64 v[2:3], v[2:3], 2, s[8:9]
	global_load_dword v106, v[2:3], off
.LBB0_839:
	s_or_b64 exec, exec, s[10:11]
	s_add_u32 s6, s6, s76
	s_addc_u32 s7, s7, s0
	v_mov_b64_e32 v[2:3], 0x8ff
	v_cmp_gt_i64_e32 vcc, s[6:7], v[2:3]
	s_cbranch_vccnz .LBB0_863
	s_and_saveexec_b64 s[10:11], s[2:3]
	s_cbranch_execz .LBB0_842
	s_ashr_i32 s12, s6, 31
	s_lshr_b32 s12, s12, 29
	s_add_i32 s12, s6, s12
	s_ashr_i32 s13, s12, 3
	s_and_b32 s12, s12, -8
	s_sub_i32 s12, s6, s12
	s_cmp_lt_i32 s12, 0
	s_movk_i32 s14, 0x121
	s_cselect_b32 s14, s14, 0x120
	s_mul_i32 s12, s12, s14
	s_add_i32 s12, s12, s13
	s_mul_hi_i32 s13, s12, 0x38e38e39
	s_lshr_b32 s14, s13, 31
	s_ashr_i32 s13, s13, 4
	s_add_i32 s13, s13, s14
	s_lshl_b32 s14, s13, 2
	s_sub_i32 s15, 0x80, s14
	s_min_i32 s15, s15, 4
	s_abs_i32 s15, s15
	v_cvt_f32_u32_e32 v1, s15
	s_sub_i32 s16, 0, s15
	s_mulk_i32 s13, 0x48
	s_sub_i32 s12, s12, s13
	v_rcp_iflag_f32_e32 v1, v1
	s_ashr_i32 s13, s12, 31
	s_abs_i32 s12, s12
	v_mov_b32_e32 v3, 0
	v_mul_f32_e32 v1, 0x4f7ffffe, v1
	v_cvt_u32_f32_e32 v1, v1
	s_nop 0
	v_readfirstlane_b32 s17, v1
	s_mul_i32 s16, s16, s17
	s_mul_hi_u32 s16, s17, s16
	s_add_i32 s17, s17, s16
	s_mul_hi_u32 s16, s12, s17
	s_mul_i32 s16, s16, s15
	s_sub_i32 s12, s12, s16
	s_sub_i32 s16, s12, s15
	s_cmp_ge_u32 s12, s15
	s_cselect_b32 s12, s16, s12
	s_sub_i32 s16, s12, s15
	s_cmp_ge_u32 s12, s15
	s_cselect_b32 s12, s16, s12
	s_xor_b32 s12, s12, s13
	s_sub_i32 s12, s12, s13
	s_add_i32 s12, s12, s14
	v_lshl_or_b32 v2, s12, 8, v153
	v_lshl_add_u64 v[2:3], v[2:3], 2, s[8:9]
	global_load_dword v107, v[2:3], off
; #define LAS __attribute__((address_space(3)))
;     __host__ __device__ bool next(int i, Unit& u) const {
;         const long L = (long)i * G + c; if (L >= nwg) return false;
;         int wgid = (int)L; { const int q = nwg / NXCD, r = nwg % NXCD, xcd = wgid % NXCD, off = wgid / NXCD; wgid = (xcd < r ? xcd * (q + 1) : r * (q + 1) + (xcd - r) * q) + off; }
;         const int nig = WGM * nN, gid = wgid / nig, fm = gid * WGM, gsz = (nM - fm) < WGM ? (nM - fm) : WGM;
;         u.pm = fm + ((wgid % nig) % gsz); u.pn = (wgid % nig) / gsz; u.idx = i; return true;
; template <class Sched>
; __device__ __forceinline__ void rstd_table(LAS float* rs, const float* ss, const Sched& S) {
;     Unit u;
;     for (int i = 0; i < 15 && S.next(i, u); ++i) if (threadIdx.x < BM) rs[i * BM + threadIdx.x] = rsqrtf(ss[u.pm * BM + threadIdx.x] * (1.0f / DM) + NORM_EPS);
; }
.LBB0_842:
	s_or_b64 exec, exec, s[10:11]
	s_add_u32 s6, s6, s76
	s_addc_u32 s7, s7, s0
	v_mov_b64_e32 v[2:3], 0x8ff
	v_cmp_gt_i64_e32 vcc, s[6:7], v[2:3]
	s_cbranch_vccnz .LBB0_863
	s_and_saveexec_b64 s[10:11], s[2:3]
	s_cbranch_execz .LBB0_845
	s_ashr_i32 s12, s6, 31
	s_lshr_b32 s12, s12, 29
	s_add_i32 s12, s6, s12
	s_ashr_i32 s13, s12, 3
	s_and_b32 s12, s12, -8
	s_sub_i32 s12, s6, s12
	s_cmp_lt_i32 s12, 0
	s_movk_i32 s14, 0x121
	s_cselect_b32 s14, s14, 0x120
	s_mul_i32 s12, s12, s14
	s_add_i32 s12, s12, s13
	s_mul_hi_i32 s13, s12, 0x38e38e39
	s_lshr_b32 s14, s13, 31
	s_ashr_i32 s13, s13, 4
	s_add_i32 s13, s13, s14
	s_lshl_b32 s14, s13, 2
	s_sub_i32 s15, 0x80, s14
	s_min_i32 s15, s15, 4
	s_abs_i32 s15, s15
	v_cvt_f32_u32_e32 v1, s15
	s_sub_i32 s16, 0, s15
	s_mulk_i32 s13, 0x48
	s_sub_i32 s12, s12, s13
	v_rcp_iflag_f32_e32 v1, v1
	s_ashr_i32 s13, s12, 31
	s_abs_i32 s12, s12
	v_mov_b32_e32 v3, 0
	v_mul_f32_e32 v1, 0x4f7ffffe, v1
	v_cvt_u32_f32_e32 v1, v1
	s_nop 0
	v_readfirstlane_b32 s17, v1
	s_mul_i32 s16, s16, s17
	s_mul_hi_u32 s16, s17, s16
	s_add_i32 s17, s17, s16
	s_mul_hi_u32 s16, s12, s17
	s_mul_i32 s16, s16, s15
	s_sub_i32 s12, s12, s16
	s_sub_i32 s16, s12, s15
	s_cmp_ge_u32 s12, s15
	s_cselect_b32 s12, s16, s12
	s_sub_i32 s16, s12, s15
	s_cmp_ge_u32 s12, s15
	s_cselect_b32 s12, s16, s12
	s_xor_b32 s12, s12, s13
	s_sub_i32 s12, s12, s13
	s_add_i32 s12, s12, s14
	v_lshl_or_b32 v2, s12, 8, v153
	v_lshl_add_u64 v[2:3], v[2:3], 2, s[8:9]
	global_load_dword v108, v[2:3], off
.LBB0_845:
	s_or_b64 exec, exec, s[10:11]
	s_add_u32 s6, s6, s76
	s_addc_u32 s7, s7, s0
	v_mov_b64_e32 v[2:3], 0x8ff
	v_cmp_gt_i64_e32 vcc, s[6:7], v[2:3]
	s_cbranch_vccnz .LBB0_863
	s_and_saveexec_b64 s[10:11], s[2:3]
	s_cbranch_execz .LBB0_848
	s_ashr_i32 s12, s6, 31
	s_lshr_b32 s12, s12, 29
	s_add_i32 s12, s6, s12
	s_ashr_i32 s13, s12, 3
	s_and_b32 s12, s12, -8
	s_sub_i32 s12, s6, s12
	s_cmp_lt_i32 s12, 0
	s_movk_i32 s14, 0x121
	s_cselect_b32 s14, s14, 0x120
	s_mul_i32 s12, s12, s14
	s_add_i32 s12, s12, s13
	s_mul_hi_i32 s13, s12, 0x38e38e39
	s_lshr_b32 s14, s13, 31
	s_ashr_i32 s13, s13, 4
	s_add_i32 s13, s13, s14
	s_lshl_b32 s14, s13, 2
	s_sub_i32 s15, 0x80, s14
	s_min_i32 s15, s15, 4
	s_abs_i32 s15, s15
	v_cvt_f32_u32_e32 v1, s15
	s_sub_i32 s16, 0, s15
	s_mulk_i32 s13, 0x48
	s_sub_i32 s12, s12, s13
	v_rcp_iflag_f32_e32 v1, v1
	s_ashr_i32 s13, s12, 31
	s_abs_i32 s12, s12
	v_mov_b32_e32 v3, 0
	v_mul_f32_e32 v1, 0x4f7ffffe, v1
	v_cvt_u32_f32_e32 v1, v1
	s_nop 0
	v_readfirstlane_b32 s17, v1
	s_mul_i32 s16, s16, s17
	s_mul_hi_u32 s16, s17, s16
	s_add_i32 s17, s17, s16
	s_mul_hi_u32 s16, s12, s17
	s_mul_i32 s16, s16, s15
	s_sub_i32 s12, s12, s16
	s_sub_i32 s16, s12, s15
	s_cmp_ge_u32 s12, s15
	s_cselect_b32 s12, s16, s12
	s_sub_i32 s16, s12, s15
	s_cmp_ge_u32 s12, s15
	s_cselect_b32 s12, s16, s12
	s_xor_b32 s12, s12, s13
	s_sub_i32 s12, s12, s13
	s_add_i32 s12, s12, s14
	v_lshl_or_b32 v2, s12, 8, v153
	v_lshl_add_u64 v[2:3], v[2:3], 2, s[8:9]
	global_load_dword v109, v[2:3], off
.LBB0_848:
	s_or_b64 exec, exec, s[10:11]
	s_add_u32 s6, s6, s76
	s_addc_u32 s7, s7, s0
	v_mov_b64_e32 v[2:3], 0x8ff
	v_cmp_gt_i64_e32 vcc, s[6:7], v[2:3]
	s_cbranch_vccnz .LBB0_863
	s_and_saveexec_b64 s[10:11], s[2:3]
	s_cbranch_execz .LBB0_851
	s_ashr_i32 s12, s6, 31
	s_lshr_b32 s12, s12, 29
	s_add_i32 s12, s6, s12
	s_ashr_i32 s13, s12, 3
	s_and_b32 s12, s12, -8
	s_sub_i32 s12, s6, s12
	s_cmp_lt_i32 s12, 0
	s_movk_i32 s14, 0x121
	s_cselect_b32 s14, s14, 0x120
	s_mul_i32 s12, s12, s14
	s_add_i32 s12, s12, s13
	s_mul_hi_i32 s13, s12, 0x38e38e39
	s_lshr_b32 s14, s13, 31
	s_ashr_i32 s13, s13, 4
	s_add_i32 s13, s13, s14
	s_lshl_b32 s14, s13, 2
	s_sub_i32 s15, 0x80, s14
	s_min_i32 s15, s15, 4
	s_abs_i32 s15, s15
	v_cvt_f32_u32_e32 v1, s15
	s_sub_i32 s16, 0, s15
	s_mulk_i32 s13, 0x48
	s_sub_i32 s12, s12, s13
	v_rcp_iflag_f32_e32 v1, v1
	s_ashr_i32 s13, s12, 31
	s_abs_i32 s12, s12
	v_mov_b32_e32 v3, 0
	v_mul_f32_e32 v1, 0x4f7ffffe, v1
	v_cvt_u32_f32_e32 v1, v1
	s_nop 0
	v_readfirstlane_b32 s17, v1
	s_mul_i32 s16, s16, s17
	s_mul_hi_u32 s16, s17, s16
	s_add_i32 s17, s17, s16
	s_mul_hi_u32 s16, s12, s17
	s_mul_i32 s16, s16, s15
	s_sub_i32 s12, s12, s16
	s_sub_i32 s16, s12, s15
	s_cmp_ge_u32 s12, s15
	s_cselect_b32 s12, s16, s12
	s_sub_i32 s16, s12, s15
	s_cmp_ge_u32 s12, s15
	s_cselect_b32 s12, s16, s12
	s_xor_b32 s12, s12, s13
	s_sub_i32 s12, s12, s13
	s_add_i32 s12, s12, s14
	v_lshl_or_b32 v2, s12, 8, v153
	v_lshl_add_u64 v[2:3], v[2:3], 2, s[8:9]
	global_load_dword v110, v[2:3], off
; #define LAS __attribute__((address_space(3)))
;     __host__ __device__ bool next(int i, Unit& u) const {
;         const long L = (long)i * G + c; if (L >= nwg) return false;
;         int wgid = (int)L; { const int q = nwg / NXCD, r = nwg % NXCD, xcd = wgid % NXCD, off = wgid / NXCD; wgid = (xcd < r ? xcd * (q + 1) : r * (q + 1) + (xcd - r) * q) + off; }
;         const int nig = WGM * nN, gid = wgid / nig, fm = gid * WGM, gsz = (nM - fm) < WGM ? (nM - fm) : WGM;
;         u.pm = fm + ((wgid % nig) % gsz); u.pn = (wgid % nig) / gsz; u.idx = i; return true;
; template <class Sched>
; __device__ __forceinline__ void rstd_table(LAS float* rs, const float* ss, const Sched& S) {
;     Unit u;
;     for (int i = 0; i < 15 && S.next(i, u); ++i) if (threadIdx.x < BM) rs[i * BM + threadIdx.x] = rsqrtf(ss[u.pm * BM + threadIdx.x] * (1.0f / DM) + NORM_EPS);
; }
.LBB0_851:
	s_or_b64 exec, exec, s[10:11]
	s_add_u32 s6, s6, s76
	s_addc_u32 s7, s7, s0
	v_mov_b64_e32 v[2:3], 0x8ff
	v_cmp_gt_i64_e32 vcc, s[6:7], v[2:3]
	s_cbranch_vccnz .LBB0_863
	s_and_saveexec_b64 s[10:11], s[2:3]
	s_cbranch_execz .LBB0_854
	s_ashr_i32 s12, s6, 31
	s_lshr_b32 s12, s12, 29
	s_add_i32 s12, s6, s12
	s_ashr_i32 s13, s12, 3
	s_and_b32 s12, s12, -8
	s_sub_i32 s12, s6, s12
	s_cmp_lt_i32 s12, 0
	s_movk_i32 s14, 0x121
	s_cselect_b32 s14, s14, 0x120
	s_mul_i32 s12, s12, s14
	s_add_i32 s12, s12, s13
	s_mul_hi_i32 s13, s12, 0x38e38e39
	s_lshr_b32 s14, s13, 31
	s_ashr_i32 s13, s13, 4
	s_add_i32 s13, s13, s14
	s_lshl_b32 s14, s13, 2
	s_sub_i32 s15, 0x80, s14
	s_min_i32 s15, s15, 4
	s_abs_i32 s15, s15
	v_cvt_f32_u32_e32 v1, s15
	s_sub_i32 s16, 0, s15
	s_mulk_i32 s13, 0x48
	s_sub_i32 s12, s12, s13
	v_rcp_iflag_f32_e32 v1, v1
	s_ashr_i32 s13, s12, 31
	s_abs_i32 s12, s12
	v_mov_b32_e32 v3, 0
	v_mul_f32_e32 v1, 0x4f7ffffe, v1
	v_cvt_u32_f32_e32 v1, v1
	s_nop 0
	v_readfirstlane_b32 s17, v1
	s_mul_i32 s16, s16, s17
	s_mul_hi_u32 s16, s17, s16
	s_add_i32 s17, s17, s16
	s_mul_hi_u32 s16, s12, s17
	s_mul_i32 s16, s16, s15
	s_sub_i32 s12, s12, s16
	s_sub_i32 s16, s12, s15
	s_cmp_ge_u32 s12, s15
	s_cselect_b32 s12, s16, s12
	s_sub_i32 s16, s12, s15
	s_cmp_ge_u32 s12, s15
	s_cselect_b32 s12, s16, s12
	s_xor_b32 s12, s12, s13
	s_sub_i32 s12, s12, s13
	s_add_i32 s12, s12, s14
	v_lshl_or_b32 v2, s12, 8, v153
	v_lshl_add_u64 v[2:3], v[2:3], 2, s[8:9]
	global_load_dword v111, v[2:3], off
.LBB0_854:
	s_or_b64 exec, exec, s[10:11]
	s_add_u32 s6, s6, s76
	s_addc_u32 s7, s7, s0
	v_mov_b64_e32 v[2:3], 0x8ff
	v_cmp_gt_i64_e32 vcc, s[6:7], v[2:3]
	s_cbranch_vccnz .LBB0_863
	s_and_saveexec_b64 s[10:11], s[2:3]
	s_cbranch_execz .LBB0_857
	s_ashr_i32 s12, s6, 31
	s_lshr_b32 s12, s12, 29
	s_add_i32 s12, s6, s12
	s_ashr_i32 s13, s12, 3
	s_and_b32 s12, s12, -8
	s_sub_i32 s12, s6, s12
	s_cmp_lt_i32 s12, 0
	s_movk_i32 s14, 0x121
	s_cselect_b32 s14, s14, 0x120
	s_mul_i32 s12, s12, s14
	s_add_i32 s12, s12, s13
	s_mul_hi_i32 s13, s12, 0x38e38e39
	s_lshr_b32 s14, s13, 31
	s_ashr_i32 s13, s13, 4
	s_add_i32 s13, s13, s14
	s_lshl_b32 s14, s13, 2
	s_sub_i32 s15, 0x80, s14
	s_min_i32 s15, s15, 4
	s_abs_i32 s15, s15
	v_cvt_f32_u32_e32 v1, s15
	s_sub_i32 s16, 0, s15
	s_mulk_i32 s13, 0x48
	s_sub_i32 s12, s12, s13
	v_rcp_iflag_f32_e32 v1, v1
	s_ashr_i32 s13, s12, 31
	s_abs_i32 s12, s12
	v_mov_b32_e32 v3, 0
	v_mul_f32_e32 v1, 0x4f7ffffe, v1
	v_cvt_u32_f32_e32 v1, v1
	s_nop 0
	v_readfirstlane_b32 s17, v1
	s_mul_i32 s16, s16, s17
	s_mul_hi_u32 s16, s17, s16
	s_add_i32 s17, s17, s16
	s_mul_hi_u32 s16, s12, s17
	s_mul_i32 s16, s16, s15
	s_sub_i32 s12, s12, s16
	s_sub_i32 s16, s12, s15
	s_cmp_ge_u32 s12, s15
	s_cselect_b32 s12, s16, s12
	s_sub_i32 s16, s12, s15
	s_cmp_ge_u32 s12, s15
	s_cselect_b32 s12, s16, s12
	s_xor_b32 s12, s12, s13
	s_sub_i32 s12, s12, s13
	s_add_i32 s12, s12, s14
	v_lshl_or_b32 v2, s12, 8, v153
	v_lshl_add_u64 v[2:3], v[2:3], 2, s[8:9]
	global_load_dword v112, v[2:3], off
.LBB0_857:
	s_or_b64 exec, exec, s[10:11]
	s_add_u32 s6, s6, s76
	s_addc_u32 s7, s7, s0
	v_mov_b64_e32 v[2:3], 0x8ff
	v_cmp_gt_i64_e32 vcc, s[6:7], v[2:3]
	s_cbranch_vccnz .LBB0_863
	s_and_saveexec_b64 s[10:11], s[2:3]
	s_cbranch_execz .LBB0_860
	s_ashr_i32 s12, s6, 31
	s_lshr_b32 s12, s12, 29
	s_add_i32 s12, s6, s12
	s_ashr_i32 s13, s12, 3
	s_and_b32 s12, s12, -8
	s_sub_i32 s12, s6, s12
	s_cmp_lt_i32 s12, 0
	s_movk_i32 s14, 0x121
	s_cselect_b32 s14, s14, 0x120
	s_mul_i32 s12, s12, s14
	s_add_i32 s12, s12, s13
	s_mul_hi_i32 s13, s12, 0x38e38e39
	s_lshr_b32 s14, s13, 31
	s_ashr_i32 s13, s13, 4
	s_add_i32 s13, s13, s14
	s_lshl_b32 s14, s13, 2
	s_sub_i32 s15, 0x80, s14
	s_min_i32 s15, s15, 4
	s_abs_i32 s15, s15
	v_cvt_f32_u32_e32 v1, s15
	s_sub_i32 s16, 0, s15
	s_mulk_i32 s13, 0x48
	s_sub_i32 s12, s12, s13
	v_rcp_iflag_f32_e32 v1, v1
	s_ashr_i32 s13, s12, 31
	s_abs_i32 s12, s12
	v_mov_b32_e32 v3, 0
	v_mul_f32_e32 v1, 0x4f7ffffe, v1
	v_cvt_u32_f32_e32 v1, v1
	s_nop 0
	v_readfirstlane_b32 s17, v1
	s_mul_i32 s16, s16, s17
	s_mul_hi_u32 s16, s17, s16
	s_add_i32 s17, s17, s16
	s_mul_hi_u32 s16, s12, s17
	s_mul_i32 s16, s16, s15
	s_sub_i32 s12, s12, s16
	s_sub_i32 s16, s12, s15
	s_cmp_ge_u32 s12, s15
	s_cselect_b32 s12, s16, s12
	s_sub_i32 s16, s12, s15
	s_cmp_ge_u32 s12, s15
	s_cselect_b32 s12, s16, s12
	s_xor_b32 s12, s12, s13
	s_sub_i32 s12, s12, s13
	s_add_i32 s12, s12, s14
	v_lshl_or_b32 v2, s12, 8, v153
	v_lshl_add_u64 v[2:3], v[2:3], 2, s[8:9]
	global_load_dword v113, v[2:3], off
.LBB0_860:
	s_or_b64 exec, exec, s[10:11]
	s_add_u32 s6, s6, s76
	s_addc_u32 s7, s7, s0
	v_mov_b64_e32 v[2:3], 0x900
	v_cmp_lt_i64_e32 vcc, s[6:7], v[2:3]
	s_and_b64 s[10:11], vcc, s[2:3]
	s_and_saveexec_b64 s[2:3], s[10:11]
	s_cbranch_execz .LBB0_862
	s_ashr_i32 s7, s6, 31
	s_lshr_b32 s7, s7, 29
	s_add_i32 s7, s6, s7
	s_ashr_i32 s10, s7, 3
	s_and_b32 s7, s7, -8
	s_sub_i32 s6, s6, s7
	s_cmp_lt_i32 s6, 0
	s_movk_i32 s7, 0x121
	s_cselect_b32 s7, s7, 0x120
	s_mul_i32 s6, s6, s7
	s_add_i32 s6, s6, s10
	s_mul_hi_i32 s7, s6, 0x38e38e39
	s_lshr_b32 s10, s7, 31
	s_ashr_i32 s7, s7, 4
	s_add_i32 s7, s7, s10
	s_lshl_b32 s10, s7, 2
	s_sub_i32 s11, 0x80, s10
	s_min_i32 s11, s11, 4
	s_abs_i32 s11, s11
	v_cvt_f32_u32_e32 v1, s11
	s_sub_i32 s12, 0, s11
	s_mulk_i32 s7, 0x48
	s_sub_i32 s6, s6, s7
	v_rcp_iflag_f32_e32 v1, v1
	s_ashr_i32 s7, s6, 31
	s_abs_i32 s6, s6
	v_mov_b32_e32 v3, 0
	v_mul_f32_e32 v1, 0x4f7ffffe, v1
	v_cvt_u32_f32_e32 v1, v1
	s_nop 0
	v_readfirstlane_b32 s13, v1
	s_mul_i32 s12, s12, s13
	s_mul_hi_u32 s12, s13, s12
	s_add_i32 s13, s13, s12
	s_mul_hi_u32 s12, s6, s13
	s_mul_i32 s12, s12, s11
	s_sub_i32 s6, s6, s12
	s_sub_i32 s12, s6, s11
	s_cmp_ge_u32 s6, s11
	s_cselect_b32 s6, s12, s6
	s_sub_i32 s12, s6, s11
	s_cmp_ge_u32 s6, s11
	s_cselect_b32 s6, s12, s6
	s_xor_b32 s6, s6, s7
	s_sub_i32 s6, s6, s7
	s_add_i32 s6, s6, s10
	v_lshl_or_b32 v2, s6, 8, v153
	v_lshl_add_u64 v[2:3], v[2:3], 2, s[8:9]
	global_load_dword v114, v[2:3], off

; template <class Sched>
; __device__ __forceinline__ void rstd_table(LAS float* rs, const float* ss, const Sched& S) {
;     ...
;     for (int i = 0; i < 15 && S.next(i, u); ++i) if (threadIdx.x < BM) rs[i * BM + threadIdx.x] = rsqrtf(ss[u.pm * BM + threadIdx.x] * (1.0f / DM) + NORM_EPS);
; template <class Epi, class Sched, bool ALIGN_EPI>
; __device__ __forceinline__ void gemm_phase(LAS unsigned char* lds, const Gemm g, const Sched& S, const Epi& E) {
;     const int tid = threadIdx.x, wid = __builtin_amdgcn_readfirstlane(tid >> 6), lane = tid & 63, wr = wid >> 2, wc = wid & 3, fr = lane & 15, fq = lane >> 4;
;     const int K = g.K, nt = K / BK;
;     unsigned voffA[2], voffB[2];
; #pragma unroll
;     for (int i = 0; i < 2; ++i) { int R, C; stage_rc(tid * 16 + i * 8192, R, C); const int Rb = (R & ~31) + perm32(R & 31);
;         voffA[i] = (unsigned)(R * g.lda + C) * 2u; voffB[i] = (unsigned)(Rb * g.ldb + C) * 2u; }
.LBB0_863:
	s_movk_i32 s23, 0x100
	v_cmp_gt_u32_e64 s[24:25], s23, v153
	s_mov_b32 s23, 0x20000
	s_nop 1
	s_and_saveexec_b64 s[30:31], s[24:25]
	v_lshl_add_u32 v115, v153, 2, s23
	s_waitcnt vmcnt(0)
	s_mov_b32 s32, 0x800000
	v_mov_b32_e32 v116, 0x358637bd
	v_fmac_f32_e32 v116, 0x3a800000, v100
	v_mul_f32_e32 v100, 0x4b800000, v116
	v_cmp_gt_f32_e32 vcc, s32, v116
	s_nop 1
	v_cndmask_b32_e32 v100, v116, v100, vcc
	v_rsq_f32_e32 v100, v100
	s_nop 0
	v_mul_f32_e32 v116, 0x45800000, v100
	v_cndmask_b32_e32 v100, v100, v116, vcc
	ds_write_b32 v115, v100
	v_mov_b32_e32 v116, 0x358637bd
	v_fmac_f32_e32 v116, 0x3a800000, v101
	v_mul_f32_e32 v101, 0x4b800000, v116
	v_cmp_gt_f32_e32 vcc, s32, v116
	s_nop 1
	v_cndmask_b32_e32 v101, v116, v101, vcc
	v_rsq_f32_e32 v101, v101
	s_nop 0
	v_mul_f32_e32 v116, 0x45800000, v101
	v_cndmask_b32_e32 v101, v101, v116, vcc
	ds_write_b32 v115, v101 offset:1024
	v_mov_b32_e32 v116, 0x358637bd
	v_fmac_f32_e32 v116, 0x3a800000, v102
	v_mul_f32_e32 v102, 0x4b800000, v116
	v_cmp_gt_f32_e32 vcc, s32, v116
	s_nop 1
	v_cndmask_b32_e32 v102, v116, v102, vcc
	v_rsq_f32_e32 v102, v102
	s_nop 0
	v_mul_f32_e32 v116, 0x45800000, v102
	v_cndmask_b32_e32 v102, v102, v116, vcc
	ds_write_b32 v115, v102 offset:2048
	v_mov_b32_e32 v116, 0x358637bd
	v_fmac_f32_e32 v116, 0x3a800000, v103
	v_mul_f32_e32 v103, 0x4b800000, v116
	v_cmp_gt_f32_e32 vcc, s32, v116
	s_nop 1
	v_cndmask_b32_e32 v103, v116, v103, vcc
	v_rsq_f32_e32 v103, v103
	s_nop 0
	v_mul_f32_e32 v116, 0x45800000, v103
	v_cndmask_b32_e32 v103, v103, v116, vcc
	ds_write_b32 v115, v103 offset:3072
	v_mov_b32_e32 v116, 0x358637bd
	v_fmac_f32_e32 v116, 0x3a800000, v104
	v_mul_f32_e32 v104, 0x4b800000, v116
	v_cmp_gt_f32_e32 vcc, s32, v116
	s_nop 1
	v_cndmask_b32_e32 v104, v116, v104, vcc
	v_rsq_f32_e32 v104, v104
	s_nop 0
	v_mul_f32_e32 v116, 0x45800000, v104
	v_cndmask_b32_e32 v104, v104, v116, vcc
	ds_write_b32 v115, v104 offset:4096
	v_mov_b32_e32 v116, 0x358637bd
	v_fmac_f32_e32 v116, 0x3a800000, v105
	v_mul_f32_e32 v105, 0x4b800000, v116
	v_cmp_gt_f32_e32 vcc, s32, v116
	s_nop 1
	v_cndmask_b32_e32 v105, v116, v105, vcc
	v_rsq_f32_e32 v105, v105
	s_nop 0
	v_mul_f32_e32 v116, 0x45800000, v105
	v_cndmask_b32_e32 v105, v105, v116, vcc
	ds_write_b32 v115, v105 offset:5120
	v_mov_b32_e32 v116, 0x358637bd
	v_fmac_f32_e32 v116, 0x3a800000, v106
	v_mul_f32_e32 v106, 0x4b800000, v116
	v_cmp_gt_f32_e32 vcc, s32, v116
	s_nop 1
	v_cndmask_b32_e32 v106, v116, v106, vcc
	v_rsq_f32_e32 v106, v106
	s_nop 0
	v_mul_f32_e32 v116, 0x45800000, v106
	v_cndmask_b32_e32 v106, v106, v116, vcc
	ds_write_b32 v115, v106 offset:6144
	v_mov_b32_e32 v116, 0x358637bd
	v_fmac_f32_e32 v116, 0x3a800000, v107
	v_mul_f32_e32 v107, 0x4b800000, v116
	v_cmp_gt_f32_e32 vcc, s32, v116
	s_nop 1
	v_cndmask_b32_e32 v107, v116, v107, vcc
	v_rsq_f32_e32 v107, v107
	s_nop 0
	v_mul_f32_e32 v116, 0x45800000, v107
	v_cndmask_b32_e32 v107, v107, v116, vcc
	ds_write_b32 v115, v107 offset:7168
	v_mov_b32_e32 v116, 0x358637bd
	v_fmac_f32_e32 v116, 0x3a800000, v108
	v_mul_f32_e32 v108, 0x4b800000, v116
	v_cmp_gt_f32_e32 vcc, s32, v116
	s_nop 1
	v_cndmask_b32_e32 v108, v116, v108, vcc
	v_rsq_f32_e32 v108, v108
	s_nop 0
	v_mul_f32_e32 v116, 0x45800000, v108
	v_cndmask_b32_e32 v108, v108, v116, vcc
	ds_write_b32 v115, v108 offset:8192
	v_mov_b32_e32 v116, 0x358637bd
	v_fmac_f32_e32 v116, 0x3a800000, v109
	v_mul_f32_e32 v109, 0x4b800000, v116
	v_cmp_gt_f32_e32 vcc, s32, v116
	s_nop 1
	v_cndmask_b32_e32 v109, v116, v109, vcc
	v_rsq_f32_e32 v109, v109
	s_nop 0
	v_mul_f32_e32 v116, 0x45800000, v109
	v_cndmask_b32_e32 v109, v109, v116, vcc
	ds_write_b32 v115, v109 offset:9216
	v_mov_b32_e32 v116, 0x358637bd
	v_fmac_f32_e32 v116, 0x3a800000, v110
	v_mul_f32_e32 v110, 0x4b800000, v116
	v_cmp_gt_f32_e32 vcc, s32, v116
	s_nop 1
	v_cndmask_b32_e32 v110, v116, v110, vcc
	v_rsq_f32_e32 v110, v110
	s_nop 0
	v_mul_f32_e32 v116, 0x45800000, v110
	v_cndmask_b32_e32 v110, v110, v116, vcc
	ds_write_b32 v115, v110 offset:10240
	v_mov_b32_e32 v116, 0x358637bd
	v_fmac_f32_e32 v116, 0x3a800000, v111
	v_mul_f32_e32 v111, 0x4b800000, v116
	v_cmp_gt_f32_e32 vcc, s32, v116
	s_nop 1
	v_cndmask_b32_e32 v111, v116, v111, vcc
	v_rsq_f32_e32 v111, v111
	s_nop 0
	v_mul_f32_e32 v116, 0x45800000, v111
	v_cndmask_b32_e32 v111, v111, v116, vcc
	ds_write_b32 v115, v111 offset:11264
	v_mov_b32_e32 v116, 0x358637bd
	v_fmac_f32_e32 v116, 0x3a800000, v112
	v_mul_f32_e32 v112, 0x4b800000, v116
	v_cmp_gt_f32_e32 vcc, s32, v116
	s_nop 1
	v_cndmask_b32_e32 v112, v116, v112, vcc
	v_rsq_f32_e32 v112, v112
	s_nop 0
	v_mul_f32_e32 v116, 0x45800000, v112
	v_cndmask_b32_e32 v112, v112, v116, vcc
	ds_write_b32 v115, v112 offset:12288
	v_mov_b32_e32 v116, 0x358637bd
	v_fmac_f32_e32 v116, 0x3a800000, v113
	v_mul_f32_e32 v113, 0x4b800000, v116
	v_cmp_gt_f32_e32 vcc, s32, v116
	s_nop 1
	v_cndmask_b32_e32 v113, v116, v113, vcc
	v_rsq_f32_e32 v113, v113
	s_nop 0
	v_mul_f32_e32 v116, 0x45800000, v113
	v_cndmask_b32_e32 v113, v113, v116, vcc
	ds_write_b32 v115, v113 offset:13312
	v_mov_b32_e32 v116, 0x358637bd
	v_fmac_f32_e32 v116, 0x3a800000, v114
	v_mul_f32_e32 v114, 0x4b800000, v116
	v_cmp_gt_f32_e32 vcc, s32, v116
	s_nop 1
	v_cndmask_b32_e32 v114, v116, v114, vcc
	v_rsq_f32_e32 v114, v114
	s_nop 0
	v_mul_f32_e32 v116, 0x45800000, v114
	v_cndmask_b32_e32 v114, v114, v116, vcc
	ds_write_b32 v115, v114 offset:14336
	s_or_b64 exec, exec, s[30:31]
	s_waitcnt vmcnt(0)
	v_cndmask_b32_e64 v0, 0, 1, s[4:5]
	v_cmp_ne_u32_e64 s[2:3], 1, v0
	s_andn2_b64 vcc, exec, s[4:5]
	v_readfirstlane_b32 s4, v153
	s_cbranch_vccnz .LBB0_865
	s_lshr_b32 s5, s1, 29
	s_add_i32 s5, s97, s5
	s_ashr_i32 s6, s5, 3
	s_and_b32 s5, s5, -8
	s_sub_i32 s5, s97, s5
	s_cmp_lt_i32 s5, 0
	s_movk_i32 s7, 0x121
	s_cselect_b32 s7, s7, 0x120
	s_mul_i32 s5, s5, s7
	s_add_i32 s5, s5, s6
	s_mul_hi_i32 s6, s5, 0x38e38e39
	s_lshr_b32 s7, s6, 31
	s_ashr_i32 s6, s6, 4
	s_add_i32 s6, s6, s7
	s_lshl_b32 s7, s6, 2
	s_mulk_i32 s6, 0x48
	s_sub_i32 s5, s5, s6
	s_bfe_i32 s6, s5, 0x80000
	s_bfe_u32 s6, s6, 0x2000d
	s_add_i32 s6, s5, s6
	s_bfe_i32 s8, s6, 0x80000
	s_and_b32 s6, s6, 0xfc
	s_sub_i32 s5, s5, s6
	s_sext_i32_i16 s8, s8
	s_sext_i32_i8 s5, s5
	s_add_i32 s6, s7, s5
	s_ashr_i32 s8, s8, 2

;     __device__ __forceinline__ void operator()(Acc& acc, const Unit& u, int wr, int wc, int fr, int fq) const {
;     ...
;         const bool gate_tile = (u.pn == 17);
; template <class Epi, class Sched, bool ALIGN_EPI>
; __device__ __forceinline__ void gemm_phase(LAS unsigned char* lds, const Gemm g, const Sched& S, const Epi& E) {
;     ...
;         const bool has_next = S.next(ui + 1, nxt);
;         const char* nA = has_next ? (const char*)g.A + (size_t)nxt.pm * tstepA : cA; const char* nB = has_next ? (const char*)g.Bt + (size_t)nxt.pn * tstepB : cB;
.LBB0_870:
	s_andn2_b64 vcc, exec, s[4:5]
	s_cmp_lg_u32 s8, 17
	s_cselect_b32 s101, 1, 0
	s_mov_b32 s7, s49
	s_mov_b32 s8, s18
	s_mov_b32 s6, s20
	s_mov_b64 s[28:29], s[24:25]
	s_mov_b64 s[26:27], s[22:23]
	s_cbranch_vccz .LBB0_960

.LBB0_873:
	s_ashr_i32 s21, s20, 31
	s_lshl_b64 s[22:23], s[20:21], 19
	s_add_u32 s22, s34, s22
	s_addc_u32 s23, s35, s23
	s_and_b64 s[24:25], s[4:5], exec
	s_cselect_b32 s21, s23, s27
	s_cselect_b32 s50, s22, s26
	s_ashr_i32 s19, s18, 31
	s_lshl_b64 s[24:25], s[18:19], 19
	s_add_u32 s24, s36, s24
	s_addc_u32 s25, s37, s25
	s_and_b64 s[30:31], s[4:5], exec
	s_cselect_b32 s19, s25, s29
	s_cselect_b32 s51, s24, s28
	s_add_u32 s26, s26, 0x40080
	s_addc_u32 s27, s27, 0
	s_add_u32 s52, s28, 0x100
	v_mov_b32_e32 v8, 0
	s_addc_u32 s53, s29, 0
	s_mov_b32 s66, -2
	s_waitcnt lgkmcnt(0)
	ds_read_b128 v[146:149], v158
	ds_read_b128 v[162:165], v158 offset:1024
	ds_read_b128 v[166:169], v158 offset:2048
	ds_read_b128 v[170:173], v158 offset:3072
	ds_read_b128 v[174:177], v159
	ds_read_b128 v[178:181], v159 offset:1024
	ds_read_b128 v[182:185], v159 offset:2048
	ds_read_b128 v[186:189], v159 offset:3072
	s_add_u32 s28, s26, 0xfffc0080
	s_addc_u32 s29, s27, -1
	s_cmp_eq_u32 s66, 12
	s_cselect_b32 s31, s21, s29
	s_cselect_b32 s30, s50, s28
	s_cselect_b32 s29, s19, s53
	s_cselect_b32 s28, s51, s52
	v_lshl_add_u64 v[222:223], s[26:27], 0, v[138:139]
	s_add_i32 m0, s9, 0xc000
	ds_read_b128 v[190:193], v160
	ds_read_b128 v[194:197], v160 offset:1024
	ds_read_b128 v[198:201], v160 offset:2048
	ds_read_b128 v[202:205], v160 offset:3072
	ds_read_b128 v[206:209], v160 offset:4096
	ds_read_b128 v[210:213], v160 offset:5120
	ds_read_b128 v[214:217], v160 offset:6144
	ds_read_b128 v[218:221], v160 offset:7168
	global_load_lds_dwordx4 v[222:223], off
	v_lshl_add_u64 v[222:223], s[26:27], 0, v[140:141]
	s_add_i32 m0, s9, 0xe000
	s_nop 0
	global_load_lds_dwordx4 v[222:223], off
	s_cmp_eq_u32 s101, 1
	s_cbranch_scc1 .Lpk874_r1
	s_waitcnt vmcnt(8)
	s_branch .Lpk874_j1
.Lpk874_r1:
	s_waitcnt vmcnt(24)
.Lpk874_j1:
	s_waitcnt lgkmcnt(0)
	s_barrier
	s_setprio 1
	s_waitcnt lgkmcnt(0)
	v_mfma_f32_16x16x32_bf16 v[116:119], v[146:149], v[190:193], 0
	v_mfma_f32_16x16x32_bf16 v[112:115], v[166:169], v[190:193], 0
	v_mfma_f32_16x16x32_bf16 v[100:103], v[146:149], v[198:201], 0
	v_mfma_f32_16x16x32_bf16 v[96:99], v[166:169], v[198:201], 0
	v_mfma_f32_16x16x32_bf16 v[84:87], v[146:149], v[206:209], 0
	v_mfma_f32_16x16x32_bf16 v[80:83], v[166:169], v[206:209], 0
	v_mfma_f32_16x16x32_bf16 v[68:71], v[146:149], v[214:217], 0
	v_mfma_f32_16x16x32_bf16 v[64:67], v[166:169], v[214:217], 0
	v_mfma_f32_16x16x32_bf16 v[116:119], v[162:165], v[194:197], v[116:119]
	v_mfma_f32_16x16x32_bf16 v[112:115], v[170:173], v[194:197], v[112:115]
	v_mfma_f32_16x16x32_bf16 v[100:103], v[162:165], v[202:205], v[100:103]
	v_mfma_f32_16x16x32_bf16 v[96:99], v[170:173], v[202:205], v[96:99]
	v_mfma_f32_16x16x32_bf16 v[84:87], v[162:165], v[210:213], v[84:87]
	v_mfma_f32_16x16x32_bf16 v[80:83], v[170:173], v[210:213], v[80:83]
	v_mfma_f32_16x16x32_bf16 v[68:71], v[162:165], v[218:221], v[68:71]
	v_mfma_f32_16x16x32_bf16 v[64:67], v[170:173], v[218:221], v[64:67]
	s_setprio 0
	s_setprio 1
	v_mfma_f32_16x16x32_bf16 v[124:127], v[174:177], v[190:193], 0
	v_mfma_f32_16x16x32_bf16 v[120:123], v[182:185], v[190:193], 0
	v_mfma_f32_16x16x32_bf16 v[108:111], v[174:177], v[198:201], 0
	v_mfma_f32_16x16x32_bf16 v[104:107], v[182:185], v[198:201], 0
	v_mfma_f32_16x16x32_bf16 v[92:95], v[174:177], v[206:209], 0
	v_mfma_f32_16x16x32_bf16 v[88:91], v[182:185], v[206:209], 0
	v_mfma_f32_16x16x32_bf16 v[76:79], v[174:177], v[214:217], 0
	v_mfma_f32_16x16x32_bf16 v[72:75], v[182:185], v[214:217], 0
	v_mfma_f32_16x16x32_bf16 v[124:127], v[178:181], v[194:197], v[124:127]
	v_mfma_f32_16x16x32_bf16 v[120:123], v[186:189], v[194:197], v[120:123]
	v_mfma_f32_16x16x32_bf16 v[108:111], v[178:181], v[202:205], v[108:111]
	v_mfma_f32_16x16x32_bf16 v[104:107], v[186:189], v[202:205], v[104:107]
	v_mfma_f32_16x16x32_bf16 v[92:95], v[178:181], v[210:213], v[92:95]
	v_mfma_f32_16x16x32_bf16 v[88:91], v[186:189], v[210:213], v[88:91]
	v_mfma_f32_16x16x32_bf16 v[76:79], v[178:181], v[218:221], v[76:79]
	v_mfma_f32_16x16x32_bf16 v[72:75], v[186:189], v[218:221], v[72:75]
	s_setprio 0
	s_barrier
	s_add_i32 s54, s44, s33
	v_lshl_add_u64 v[222:223], s[28:29], 0, v[130:131]
	s_mov_b32 m0, s54
	ds_read_b128 v[190:193], v160 offset:16384
	ds_read_b128 v[194:197], v160 offset:17408
	global_load_lds_dwordx4 v[222:223], off
	s_add_i32 m0, s54, 0x2000
	s_add_u32 s70, s28, 0x40000
	v_lshl_add_u64 v[224:225], s[28:29], 0, v[134:135]
	s_addc_u32 s71, s29, 0
	s_add_i32 s54, s45, s33
	ds_read_b128 v[198:201], v160 offset:18432
	ds_read_b128 v[202:205], v160 offset:19456
	global_load_lds_dwordx4 v[224:225], off
	v_lshl_add_u64 v[226:227], s[70:71], 0, v[130:131]
	s_mov_b32 m0, s54
	v_lshl_add_u64 v[228:229], s[30:31], 0, v[132:133]
	ds_read_b128 v[206:209], v160 offset:20480
	global_load_lds_dwordx4 v[226:227], off
	v_lshl_add_u64 v[226:227], s[70:71], 0, v[134:135]
	s_add_i32 m0, s54, 0x2000
	ds_read_b128 v[210:213], v160 offset:21504
	global_load_lds_dwordx4 v[226:227], off
	v_lshl_add_u64 v[226:227], s[30:31], 0, v[128:129]
	s_mov_b32 m0, s9
	ds_read_b128 v[214:217], v160 offset:22528
	global_load_lds_dwordx4 v[226:227], off
	s_mov_b32 m0, s38
	ds_read_b128 v[218:221], v160 offset:23552
	global_load_lds_dwordx4 v[228:229], off
	s_cmp_eq_u32 s101, 1
	s_cbranch_scc1 .Lpk874_r2
	s_waitcnt vmcnt(8)
	s_branch .Lpk874_j2

.Lpk874_j2:
	s_mov_b32 s101, 0
	s_waitcnt lgkmcnt(0)
	s_barrier
	s_setprio 1
	s_waitcnt lgkmcnt(0)
	v_mfma_f32_16x16x32_bf16 v[52:55], v[146:149], v[190:193], 0
	v_mfma_f32_16x16x32_bf16 v[48:51], v[166:169], v[190:193], 0
	v_mfma_f32_16x16x32_bf16 v[36:39], v[146:149], v[198:201], 0
	v_mfma_f32_16x16x32_bf16 v[32:35], v[166:169], v[198:201], 0
	v_mfma_f32_16x16x32_bf16 v[20:23], v[146:149], v[206:209], 0
	v_mfma_f32_16x16x32_bf16 v[16:19], v[166:169], v[206:209], 0
	v_mfma_f32_16x16x32_bf16 v[4:7], v[146:149], v[214:217], 0
	v_mfma_f32_16x16x32_bf16 v[0:3], v[166:169], v[214:217], 0
	v_mfma_f32_16x16x32_bf16 v[52:55], v[162:165], v[194:197], v[52:55]
	v_mfma_f32_16x16x32_bf16 v[48:51], v[170:173], v[194:197], v[48:51]
	v_mfma_f32_16x16x32_bf16 v[36:39], v[162:165], v[202:205], v[36:39]
	v_mfma_f32_16x16x32_bf16 v[32:35], v[170:173], v[202:205], v[32:35]
	v_mfma_f32_16x16x32_bf16 v[20:23], v[162:165], v[210:213], v[20:23]
	v_mfma_f32_16x16x32_bf16 v[16:19], v[170:173], v[210:213], v[16:19]
	v_mfma_f32_16x16x32_bf16 v[4:7], v[162:165], v[218:221], v[4:7]
	v_mfma_f32_16x16x32_bf16 v[0:3], v[170:173], v[218:221], v[0:3]
	s_setprio 0
	s_setprio 1
	v_mfma_f32_16x16x32_bf16 v[60:63], v[174:177], v[190:193], 0
	v_mfma_f32_16x16x32_bf16 v[56:59], v[182:185], v[190:193], 0
	v_mfma_f32_16x16x32_bf16 v[44:47], v[174:177], v[198:201], 0
	v_mfma_f32_16x16x32_bf16 v[40:43], v[182:185], v[198:201], 0
	v_mfma_f32_16x16x32_bf16 v[28:31], v[174:177], v[206:209], 0
	v_mfma_f32_16x16x32_bf16 v[24:27], v[182:185], v[206:209], 0
	v_mfma_f32_16x16x32_bf16 v[12:15], v[174:177], v[214:217], 0
	v_mfma_f32_16x16x32_bf16 v[8:11], v[182:185], v[214:217], 0
	v_mfma_f32_16x16x32_bf16 v[60:63], v[178:181], v[194:197], v[60:63]
	v_mfma_f32_16x16x32_bf16 v[56:59], v[186:189], v[194:197], v[56:59]
	v_mfma_f32_16x16x32_bf16 v[44:47], v[178:181], v[202:205], v[44:47]
	v_mfma_f32_16x16x32_bf16 v[40:43], v[186:189], v[202:205], v[40:43]
	v_mfma_f32_16x16x32_bf16 v[28:31], v[178:181], v[210:213], v[28:31]
	v_mfma_f32_16x16x32_bf16 v[24:27], v[186:189], v[210:213], v[24:27]
	v_mfma_f32_16x16x32_bf16 v[12:15], v[178:181], v[218:221], v[12:15]
	v_mfma_f32_16x16x32_bf16 v[8:11], v[186:189], v[218:221], v[8:11]
	s_setprio 0
	s_barrier
	s_branch .Lpk874_seg3

; #define PG8_WAIT_V(n) asm volatile("s_waitcnt vmcnt(" #n ")" ::: "memory")
; #define PG8_BAR __builtin_amdgcn_s_barrier()
; template <class Epi, class Sched, bool ALIGN_EPI>
; __device__ __forceinline__ void gemm_phase(LAS unsigned char* lds, const Gemm g, const Sched& S, const Epi& E) {
;     ...
;         if constexpr (ALIGN_EPI) { if (wr == 1) PG8_BAR; }
;     ...
;     PG8_WAIT_V(0);
;     if constexpr (!ALIGN_EPI) { if (wr == 0) PG8_BAR; }
;     PG8_BAR;
.LBB0_958:
	s_andn2_b64 vcc, exec, s[10:11]
	s_cbranch_vccnz .LBB0_869
	s_barrier
	s_branch .LBB0_869
.LBB0_960:
	s_mov_b32 s101, 0
	s_waitcnt vmcnt(0)
	s_barrier

; #define LAS __attribute__((address_space(3)))
;     __host__ __device__ bool next(int i, Unit& u) const {
;         const long L = (long)i * G + c; if (L >= nwg) return false;
;         int wgid = (int)L; { const int q = nwg / NXCD, r = nwg % NXCD, xcd = wgid % NXCD, off = wgid / NXCD; wgid = (xcd < r ? xcd * (q + 1) : r * (q + 1) + (xcd - r) * q) + off; }
;         const int nig = WGM * nN, gid = wgid / nig, fm = gid * WGM, gsz = (nM - fm) < WGM ? (nM - fm) : WGM;
;         u.pm = fm + ((wgid % nig) % gsz); u.pn = (wgid % nig) / gsz; u.idx = i; return true;
; template <class Sched>
; __device__ __forceinline__ void rstd_table(LAS float* rs, const float* ss, const Sched& S) {
;     Unit u;
;     for (int i = 0; i < 15 && S.next(i, u); ++i) if (threadIdx.x < BM) rs[i * BM + threadIdx.x] = rsqrtf(ss[u.pm * BM + threadIdx.x] * (1.0f / DM) + NORM_EPS);
; }
.LBB0_1558:
	s_cmp_lt_i32 s88, 8
	s_cselect_b64 s[0:1], -1, 0
	s_cmp_gt_i32 s89, 7
	s_cselect_b64 s[2:3], -1, 0
	s_and_b64 s[0:1], s[0:1], s[2:3]
	s_andn2_b64 vcc, exec, s[0:1]
	s_waitcnt lgkmcnt(0)
	s_cbranch_vccnz .LBB0_1620
	s_ashr_i32 s0, s76, 31
	s_ashr_i32 s1, s97, 31
	s_cmpk_lt_i32 s97, 0xb00
	s_cselect_b64 s[4:5], -1, 0
	s_cmpk_gt_i32 s97, 0xaff
	s_cbranch_scc1 .LBB0_1604
	s_movk_i32 s2, 0x100
	s_add_i32 s8, 0, 0x20000
	v_cmp_gt_u32_e64 s[2:3], s2, v153
	v_lshl_add_u32 v0, v153, 2, s8
	s_and_saveexec_b64 s[8:9], s[2:3]
	s_cbranch_execz .LBB0_1562
	s_lshr_b32 s10, s1, 29
	s_add_i32 s10, s97, s10
	s_and_b32 s11, s10, -8
	s_sub_i32 s11, s97, s11
	s_cmp_lt_i32 s11, 0
	s_movk_i32 s12, 0x161
	s_cselect_b32 s12, s12, 0x160
	s_mul_i32 s11, s11, s12
	s_ashr_i32 s10, s10, 3
	s_add_i32 s11, s11, s10
	s_mul_hi_i32 s10, s11, 0x2e8ba2e9
	s_lshr_b32 s12, s10, 31
	s_ashr_i32 s10, s10, 4
	s_add_i32 s10, s10, s12
	s_lshl_b32 s12, s10, 2
	s_sub_i32 s13, 0x80, s12
	s_min_i32 s13, s13, 4
	s_abs_i32 s13, s13
	v_cvt_f32_u32_e32 v1, s13
	s_sub_i32 s14, 0, s13
	s_mulk_i32 s10, 0x58
	s_sub_i32 s10, s11, s10
	v_rcp_iflag_f32_e32 v1, v1
	s_ashr_i32 s11, s10, 31
	s_abs_i32 s10, s10
	v_mov_b32_e32 v3, 0
	v_mul_f32_e32 v1, 0x4f7ffffe, v1
	v_cvt_u32_f32_e32 v1, v1
	s_nop 0
	v_readfirstlane_b32 s15, v1
	s_mul_i32 s14, s14, s15
	s_mul_hi_u32 s14, s15, s14
	s_add_i32 s15, s15, s14
	s_mul_hi_u32 s14, s10, s15
	s_mul_i32 s14, s14, s13
	s_sub_i32 s10, s10, s14
	s_sub_i32 s14, s10, s13
	s_cmp_ge_u32 s10, s13
	s_cselect_b32 s10, s14, s10
	s_sub_i32 s14, s10, s13
	s_cmp_ge_u32 s10, s13
	s_cselect_b32 s10, s14, s10
	s_xor_b32 s10, s10, s11
	s_sub_i32 s10, s10, s11
	s_add_i32 s10, s10, s12
	v_lshl_or_b32 v2, s10, 8, v153
	v_lshl_add_u64 v[2:3], v[2:3], 2, s[6:7]
	global_load_dword v100, v[2:3], off
.LBB0_1562:
	s_or_b64 exec, exec, s[8:9]
	s_add_u32 s8, s76, s97
	s_addc_u32 s9, s0, s1
	v_mov_b64_e32 v[2:3], 0xaff
	v_cmp_gt_i64_e32 vcc, s[8:9], v[2:3]
	s_cbranch_vccnz .LBB0_1604
	s_and_saveexec_b64 s[10:11], s[2:3]
	s_cbranch_execz .LBB0_1565
	s_ashr_i32 s12, s8, 31
	s_lshr_b32 s12, s12, 29
	s_add_i32 s12, s8, s12
	s_ashr_i32 s13, s12, 3
	s_and_b32 s12, s12, -8
	s_sub_i32 s12, s8, s12
	s_cmp_lt_i32 s12, 0
	s_movk_i32 s14, 0x161
	s_cselect_b32 s14, s14, 0x160
	s_mul_i32 s12, s12, s14
	s_add_i32 s12, s12, s13
	s_mul_hi_i32 s13, s12, 0x2e8ba2e9
	s_lshr_b32 s14, s13, 31
	s_ashr_i32 s13, s13, 4
	s_add_i32 s13, s13, s14
	s_lshl_b32 s14, s13, 2
	s_sub_i32 s15, 0x80, s14
	s_min_i32 s15, s15, 4
	s_abs_i32 s15, s15
	v_cvt_f32_u32_e32 v1, s15
	s_sub_i32 s16, 0, s15
	s_mulk_i32 s13, 0x58
	s_sub_i32 s12, s12, s13
	v_rcp_iflag_f32_e32 v1, v1
	s_ashr_i32 s13, s12, 31
	s_abs_i32 s12, s12
	v_mov_b32_e32 v3, 0
	v_mul_f32_e32 v1, 0x4f7ffffe, v1
	v_cvt_u32_f32_e32 v1, v1
	s_nop 0
	v_readfirstlane_b32 s17, v1
	s_mul_i32 s16, s16, s17
	s_mul_hi_u32 s16, s17, s16
	s_add_i32 s17, s17, s16
	s_mul_hi_u32 s16, s12, s17
	s_mul_i32 s16, s16, s15
	s_sub_i32 s12, s12, s16
	s_sub_i32 s16, s12, s15
	s_cmp_ge_u32 s12, s15
	s_cselect_b32 s12, s16, s12
	s_sub_i32 s16, s12, s15
	s_cmp_ge_u32 s12, s15
	s_cselect_b32 s12, s16, s12
	s_xor_b32 s12, s12, s13
	s_sub_i32 s12, s12, s13
	s_add_i32 s12, s12, s14
	v_lshl_or_b32 v2, s12, 8, v153
	v_lshl_add_u64 v[2:3], v[2:3], 2, s[6:7]
	global_load_dword v101, v[2:3], off
.LBB0_1565:
	s_or_b64 exec, exec, s[10:11]
	s_add_u32 s8, s8, s76
	s_addc_u32 s9, s9, s0
	v_mov_b64_e32 v[2:3], 0xaff
	v_cmp_gt_i64_e32 vcc, s[8:9], v[2:3]
	s_cbranch_vccnz .LBB0_1604
	s_and_saveexec_b64 s[10:11], s[2:3]
	s_cbranch_execz .LBB0_1568
	s_ashr_i32 s12, s8, 31
	s_lshr_b32 s12, s12, 29
	s_add_i32 s12, s8, s12
	s_ashr_i32 s13, s12, 3
	s_and_b32 s12, s12, -8
	s_sub_i32 s12, s8, s12
	s_cmp_lt_i32 s12, 0
	s_movk_i32 s14, 0x161
	s_cselect_b32 s14, s14, 0x160
	s_mul_i32 s12, s12, s14
	s_add_i32 s12, s12, s13
	s_mul_hi_i32 s13, s12, 0x2e8ba2e9
	s_lshr_b32 s14, s13, 31
	s_ashr_i32 s13, s13, 4
	s_add_i32 s13, s13, s14
	s_lshl_b32 s14, s13, 2
	s_sub_i32 s15, 0x80, s14
	s_min_i32 s15, s15, 4
	s_abs_i32 s15, s15
	v_cvt_f32_u32_e32 v1, s15
	s_sub_i32 s16, 0, s15
	s_mulk_i32 s13, 0x58
	s_sub_i32 s12, s12, s13
	v_rcp_iflag_f32_e32 v1, v1
	s_ashr_i32 s13, s12, 31
	s_abs_i32 s12, s12
	v_mov_b32_e32 v3, 0
	v_mul_f32_e32 v1, 0x4f7ffffe, v1
	v_cvt_u32_f32_e32 v1, v1
	s_nop 0
	v_readfirstlane_b32 s17, v1
	s_mul_i32 s16, s16, s17
	s_mul_hi_u32 s16, s17, s16
	s_add_i32 s17, s17, s16
	s_mul_hi_u32 s16, s12, s17
	s_mul_i32 s16, s16, s15
	s_sub_i32 s12, s12, s16
	s_sub_i32 s16, s12, s15
	s_cmp_ge_u32 s12, s15
	s_cselect_b32 s12, s16, s12
	s_sub_i32 s16, s12, s15
	s_cmp_ge_u32 s12, s15
	s_cselect_b32 s12, s16, s12
	s_xor_b32 s12, s12, s13
	s_sub_i32 s12, s12, s13
	s_add_i32 s12, s12, s14
	v_lshl_or_b32 v2, s12, 8, v153
	v_lshl_add_u64 v[2:3], v[2:3], 2, s[6:7]
	global_load_dword v102, v[2:3], off
.LBB0_1568:
	s_or_b64 exec, exec, s[10:11]
	s_add_u32 s8, s8, s76
	s_addc_u32 s9, s9, s0
	v_mov_b64_e32 v[2:3], 0xaff
	v_cmp_gt_i64_e32 vcc, s[8:9], v[2:3]
	s_cbranch_vccnz .LBB0_1604
	s_and_saveexec_b64 s[10:11], s[2:3]
	s_cbranch_execz .LBB0_1571
	s_ashr_i32 s12, s8, 31
	s_lshr_b32 s12, s12, 29
	s_add_i32 s12, s8, s12
	s_ashr_i32 s13, s12, 3
	s_and_b32 s12, s12, -8
	s_sub_i32 s12, s8, s12
	s_cmp_lt_i32 s12, 0
	s_movk_i32 s14, 0x161
	s_cselect_b32 s14, s14, 0x160
	s_mul_i32 s12, s12, s14
	s_add_i32 s12, s12, s13
	s_mul_hi_i32 s13, s12, 0x2e8ba2e9
	s_lshr_b32 s14, s13, 31
	s_ashr_i32 s13, s13, 4
	s_add_i32 s13, s13, s14
	s_lshl_b32 s14, s13, 2
	s_sub_i32 s15, 0x80, s14
	s_min_i32 s15, s15, 4
	s_abs_i32 s15, s15
	v_cvt_f32_u32_e32 v1, s15
	s_sub_i32 s16, 0, s15
	s_mulk_i32 s13, 0x58
	s_sub_i32 s12, s12, s13
	v_rcp_iflag_f32_e32 v1, v1
	s_ashr_i32 s13, s12, 31
	s_abs_i32 s12, s12
	v_mov_b32_e32 v3, 0
	v_mul_f32_e32 v1, 0x4f7ffffe, v1
	v_cvt_u32_f32_e32 v1, v1
	s_nop 0
	v_readfirstlane_b32 s17, v1
	s_mul_i32 s16, s16, s17
	s_mul_hi_u32 s16, s17, s16
	s_add_i32 s17, s17, s16
	s_mul_hi_u32 s16, s12, s17
	s_mul_i32 s16, s16, s15
	s_sub_i32 s12, s12, s16
	s_sub_i32 s16, s12, s15
	s_cmp_ge_u32 s12, s15
	s_cselect_b32 s12, s16, s12
	s_sub_i32 s16, s12, s15
	s_cmp_ge_u32 s12, s15
	s_cselect_b32 s12, s16, s12
	s_xor_b32 s12, s12, s13
	s_sub_i32 s12, s12, s13
	s_add_i32 s12, s12, s14
	v_lshl_or_b32 v2, s12, 8, v153
	v_lshl_add_u64 v[2:3], v[2:3], 2, s[6:7]
	global_load_dword v103, v[2:3], off
;     __host__ __device__ bool next(int i, Unit& u) const {
;         const long L = (long)i * G + c; if (L >= nwg) return false;
;         int wgid = (int)L; { const int q = nwg / NXCD, r = nwg % NXCD, xcd = wgid % NXCD, off = wgid / NXCD; wgid = (xcd < r ? xcd * (q + 1) : r * (q + 1) + (xcd - r) * q) + off; }
;         const int nig = WGM * nN, gid = wgid / nig, fm = gid * WGM, gsz = (nM - fm) < WGM ? (nM - fm) : WGM;
;         u.pm = fm + ((wgid % nig) % gsz); u.pn = (wgid % nig) / gsz; u.idx = i; return true;
; template <class Sched>
; __device__ __forceinline__ void rstd_table(LAS float* rs, const float* ss, const Sched& S) {
;     ...
;     for (int i = 0; i < 15 && S.next(i, u); ++i) if (threadIdx.x < BM) rs[i * BM + threadIdx.x] = rsqrtf(ss[u.pm * BM + threadIdx.x] * (1.0f / DM) + NORM_EPS);
.LBB0_1571:
	s_or_b64 exec, exec, s[10:11]
	s_add_u32 s8, s8, s76
	s_addc_u32 s9, s9, s0
	v_mov_b64_e32 v[2:3], 0xaff
	v_cmp_gt_i64_e32 vcc, s[8:9], v[2:3]
	s_cbranch_vccnz .LBB0_1604
	s_and_saveexec_b64 s[10:11], s[2:3]
	s_cbranch_execz .LBB0_1574
	s_ashr_i32 s12, s8, 31
	s_lshr_b32 s12, s12, 29
	s_add_i32 s12, s8, s12
	s_ashr_i32 s13, s12, 3
	s_and_b32 s12, s12, -8
	s_sub_i32 s12, s8, s12
	s_cmp_lt_i32 s12, 0
	s_movk_i32 s14, 0x161
	s_cselect_b32 s14, s14, 0x160
	s_mul_i32 s12, s12, s14
	s_add_i32 s12, s12, s13
	s_mul_hi_i32 s13, s12, 0x2e8ba2e9
	s_lshr_b32 s14, s13, 31
	s_ashr_i32 s13, s13, 4
	s_add_i32 s13, s13, s14
	s_lshl_b32 s14, s13, 2
	s_sub_i32 s15, 0x80, s14
	s_min_i32 s15, s15, 4
	s_abs_i32 s15, s15
	v_cvt_f32_u32_e32 v1, s15
	s_sub_i32 s16, 0, s15
	s_mulk_i32 s13, 0x58
	s_sub_i32 s12, s12, s13
	v_rcp_iflag_f32_e32 v1, v1
	s_ashr_i32 s13, s12, 31
	s_abs_i32 s12, s12
	v_mov_b32_e32 v3, 0
	v_mul_f32_e32 v1, 0x4f7ffffe, v1
	v_cvt_u32_f32_e32 v1, v1
	s_nop 0
	v_readfirstlane_b32 s17, v1
	s_mul_i32 s16, s16, s17
	s_mul_hi_u32 s16, s17, s16
	s_add_i32 s17, s17, s16
	s_mul_hi_u32 s16, s12, s17
	s_mul_i32 s16, s16, s15
	s_sub_i32 s12, s12, s16
	s_sub_i32 s16, s12, s15
	s_cmp_ge_u32 s12, s15
	s_cselect_b32 s12, s16, s12
	s_sub_i32 s16, s12, s15
	s_cmp_ge_u32 s12, s15
	s_cselect_b32 s12, s16, s12
	s_xor_b32 s12, s12, s13
	s_sub_i32 s12, s12, s13
	s_add_i32 s12, s12, s14
	v_lshl_or_b32 v2, s12, 8, v153
	v_lshl_add_u64 v[2:3], v[2:3], 2, s[6:7]
	global_load_dword v104, v[2:3], off
.LBB0_1574:
	s_or_b64 exec, exec, s[10:11]
	s_add_u32 s8, s8, s76
	s_addc_u32 s9, s9, s0
	v_mov_b64_e32 v[2:3], 0xaff
	v_cmp_gt_i64_e32 vcc, s[8:9], v[2:3]
	s_cbranch_vccnz .LBB0_1604
	s_and_saveexec_b64 s[10:11], s[2:3]
	s_cbranch_execz .LBB0_1577
	s_ashr_i32 s12, s8, 31
	s_lshr_b32 s12, s12, 29
	s_add_i32 s12, s8, s12
	s_ashr_i32 s13, s12, 3
	s_and_b32 s12, s12, -8
	s_sub_i32 s12, s8, s12
	s_cmp_lt_i32 s12, 0
	s_movk_i32 s14, 0x161
	s_cselect_b32 s14, s14, 0x160
	s_mul_i32 s12, s12, s14
	s_add_i32 s12, s12, s13
	s_mul_hi_i32 s13, s12, 0x2e8ba2e9
	s_lshr_b32 s14, s13, 31
	s_ashr_i32 s13, s13, 4
	s_add_i32 s13, s13, s14
	s_lshl_b32 s14, s13, 2
	s_sub_i32 s15, 0x80, s14
	s_min_i32 s15, s15, 4
	s_abs_i32 s15, s15
	v_cvt_f32_u32_e32 v1, s15
	s_sub_i32 s16, 0, s15
	s_mulk_i32 s13, 0x58
	s_sub_i32 s12, s12, s13
	v_rcp_iflag_f32_e32 v1, v1
	s_ashr_i32 s13, s12, 31
	s_abs_i32 s12, s12
	v_mov_b32_e32 v3, 0
	v_mul_f32_e32 v1, 0x4f7ffffe, v1
	v_cvt_u32_f32_e32 v1, v1
	s_nop 0
	v_readfirstlane_b32 s17, v1
	s_mul_i32 s16, s16, s17
	s_mul_hi_u32 s16, s17, s16
	s_add_i32 s17, s17, s16
	s_mul_hi_u32 s16, s12, s17
	s_mul_i32 s16, s16, s15
	s_sub_i32 s12, s12, s16
	s_sub_i32 s16, s12, s15
	s_cmp_ge_u32 s12, s15
	s_cselect_b32 s12, s16, s12
	s_sub_i32 s16, s12, s15
	s_cmp_ge_u32 s12, s15
	s_cselect_b32 s12, s16, s12
	s_xor_b32 s12, s12, s13
	s_sub_i32 s12, s12, s13
	s_add_i32 s12, s12, s14
	v_lshl_or_b32 v2, s12, 8, v153
	v_lshl_add_u64 v[2:3], v[2:3], 2, s[6:7]
	global_load_dword v105, v[2:3], off
.LBB0_1577:
	s_or_b64 exec, exec, s[10:11]
	s_add_u32 s8, s8, s76
	s_addc_u32 s9, s9, s0
	v_mov_b64_e32 v[2:3], 0xaff
	v_cmp_gt_i64_e32 vcc, s[8:9], v[2:3]
	s_cbranch_vccnz .LBB0_1604
	s_and_saveexec_b64 s[10:11], s[2:3]
	s_cbranch_execz .LBB0_1580
	s_ashr_i32 s12, s8, 31
	s_lshr_b32 s12, s12, 29
	s_add_i32 s12, s8, s12
	s_ashr_i32 s13, s12, 3
	s_and_b32 s12, s12, -8
	s_sub_i32 s12, s8, s12
	s_cmp_lt_i32 s12, 0
	s_movk_i32 s14, 0x161
	s_cselect_b32 s14, s14, 0x160
	s_mul_i32 s12, s12, s14
	s_add_i32 s12, s12, s13
	s_mul_hi_i32 s13, s12, 0x2e8ba2e9
	s_lshr_b32 s14, s13, 31
	s_ashr_i32 s13, s13, 4
	s_add_i32 s13, s13, s14
	s_lshl_b32 s14, s13, 2
	s_sub_i32 s15, 0x80, s14
	s_min_i32 s15, s15, 4
	s_abs_i32 s15, s15
	v_cvt_f32_u32_e32 v1, s15
	s_sub_i32 s16, 0, s15
	s_mulk_i32 s13, 0x58
	s_sub_i32 s12, s12, s13
	v_rcp_iflag_f32_e32 v1, v1
	s_ashr_i32 s13, s12, 31
	s_abs_i32 s12, s12
	v_mov_b32_e32 v3, 0
	v_mul_f32_e32 v1, 0x4f7ffffe, v1
	v_cvt_u32_f32_e32 v1, v1
	s_nop 0
	v_readfirstlane_b32 s17, v1
	s_mul_i32 s16, s16, s17
	s_mul_hi_u32 s16, s17, s16
	s_add_i32 s17, s17, s16
	s_mul_hi_u32 s16, s12, s17
	s_mul_i32 s16, s16, s15
	s_sub_i32 s12, s12, s16
	s_sub_i32 s16, s12, s15
	s_cmp_ge_u32 s12, s15
	s_cselect_b32 s12, s16, s12
	s_sub_i32 s16, s12, s15
	s_cmp_ge_u32 s12, s15
	s_cselect_b32 s12, s16, s12
	s_xor_b32 s12, s12, s13
	s_sub_i32 s12, s12, s13
	s_add_i32 s12, s12, s14
	v_lshl_or_b32 v2, s12, 8, v153
	v_lshl_add_u64 v[2:3], v[2:3], 2, s[6:7]
	global_load_dword v106, v[2:3], off
.LBB0_1580:
	s_or_b64 exec, exec, s[10:11]
	s_add_u32 s8, s8, s76
	s_addc_u32 s9, s9, s0
	v_mov_b64_e32 v[2:3], 0xaff
	v_cmp_gt_i64_e32 vcc, s[8:9], v[2:3]
	s_cbranch_vccnz .LBB0_1604
	s_and_saveexec_b64 s[10:11], s[2:3]
	s_cbranch_execz .LBB0_1583
	s_ashr_i32 s12, s8, 31
	s_lshr_b32 s12, s12, 29
	s_add_i32 s12, s8, s12
	s_ashr_i32 s13, s12, 3
	s_and_b32 s12, s12, -8
	s_sub_i32 s12, s8, s12
	s_cmp_lt_i32 s12, 0
	s_movk_i32 s14, 0x161
	s_cselect_b32 s14, s14, 0x160
	s_mul_i32 s12, s12, s14
	s_add_i32 s12, s12, s13
	s_mul_hi_i32 s13, s12, 0x2e8ba2e9
	s_lshr_b32 s14, s13, 31
	s_ashr_i32 s13, s13, 4
	s_add_i32 s13, s13, s14
	s_lshl_b32 s14, s13, 2
	s_sub_i32 s15, 0x80, s14
	s_min_i32 s15, s15, 4
	s_abs_i32 s15, s15
	v_cvt_f32_u32_e32 v1, s15
	s_sub_i32 s16, 0, s15
	s_mulk_i32 s13, 0x58
	s_sub_i32 s12, s12, s13
	v_rcp_iflag_f32_e32 v1, v1
	s_ashr_i32 s13, s12, 31
	s_abs_i32 s12, s12
	v_mov_b32_e32 v3, 0
	v_mul_f32_e32 v1, 0x4f7ffffe, v1
	v_cvt_u32_f32_e32 v1, v1
	s_nop 0
	v_readfirstlane_b32 s17, v1
	s_mul_i32 s16, s16, s17
	s_mul_hi_u32 s16, s17, s16
	s_add_i32 s17, s17, s16
	s_mul_hi_u32 s16, s12, s17
	s_mul_i32 s16, s16, s15
	s_sub_i32 s12, s12, s16
	s_sub_i32 s16, s12, s15
	s_cmp_ge_u32 s12, s15
	s_cselect_b32 s12, s16, s12
	s_sub_i32 s16, s12, s15
	s_cmp_ge_u32 s12, s15
	s_cselect_b32 s12, s16, s12
	s_xor_b32 s12, s12, s13
	s_sub_i32 s12, s12, s13
	s_add_i32 s12, s12, s14
	v_lshl_or_b32 v2, s12, 8, v153
	v_lshl_add_u64 v[2:3], v[2:3], 2, s[6:7]
	global_load_dword v107, v[2:3], off
;     __host__ __device__ bool next(int i, Unit& u) const {
;         const long L = (long)i * G + c; if (L >= nwg) return false;
;         int wgid = (int)L; { const int q = nwg / NXCD, r = nwg % NXCD, xcd = wgid % NXCD, off = wgid / NXCD; wgid = (xcd < r ? xcd * (q + 1) : r * (q + 1) + (xcd - r) * q) + off; }
;         const int nig = WGM * nN, gid = wgid / nig, fm = gid * WGM, gsz = (nM - fm) < WGM ? (nM - fm) : WGM;
;         u.pm = fm + ((wgid % nig) % gsz); u.pn = (wgid % nig) / gsz; u.idx = i; return true;
; template <class Sched>
; __device__ __forceinline__ void rstd_table(LAS float* rs, const float* ss, const Sched& S) {
;     ...
;     for (int i = 0; i < 15 && S.next(i, u); ++i) if (threadIdx.x < BM) rs[i * BM + threadIdx.x] = rsqrtf(ss[u.pm * BM + threadIdx.x] * (1.0f / DM) + NORM_EPS);
.LBB0_1583:
	s_or_b64 exec, exec, s[10:11]
	s_add_u32 s8, s8, s76
	s_addc_u32 s9, s9, s0
	v_mov_b64_e32 v[2:3], 0xaff
	v_cmp_gt_i64_e32 vcc, s[8:9], v[2:3]
	s_cbranch_vccnz .LBB0_1604
	s_and_saveexec_b64 s[10:11], s[2:3]
	s_cbranch_execz .LBB0_1586
	s_ashr_i32 s12, s8, 31
	s_lshr_b32 s12, s12, 29
	s_add_i32 s12, s8, s12
	s_ashr_i32 s13, s12, 3
	s_and_b32 s12, s12, -8
	s_sub_i32 s12, s8, s12
	s_cmp_lt_i32 s12, 0
	s_movk_i32 s14, 0x161
	s_cselect_b32 s14, s14, 0x160
	s_mul_i32 s12, s12, s14
	s_add_i32 s12, s12, s13
	s_mul_hi_i32 s13, s12, 0x2e8ba2e9
	s_lshr_b32 s14, s13, 31
	s_ashr_i32 s13, s13, 4
	s_add_i32 s13, s13, s14
	s_lshl_b32 s14, s13, 2
	s_sub_i32 s15, 0x80, s14
	s_min_i32 s15, s15, 4
	s_abs_i32 s15, s15
	v_cvt_f32_u32_e32 v1, s15
	s_sub_i32 s16, 0, s15
	s_mulk_i32 s13, 0x58
	s_sub_i32 s12, s12, s13
	v_rcp_iflag_f32_e32 v1, v1
	s_ashr_i32 s13, s12, 31
	s_abs_i32 s12, s12
	v_mov_b32_e32 v3, 0
	v_mul_f32_e32 v1, 0x4f7ffffe, v1
	v_cvt_u32_f32_e32 v1, v1
	s_nop 0
	v_readfirstlane_b32 s17, v1
	s_mul_i32 s16, s16, s17
	s_mul_hi_u32 s16, s17, s16
	s_add_i32 s17, s17, s16
	s_mul_hi_u32 s16, s12, s17
	s_mul_i32 s16, s16, s15
	s_sub_i32 s12, s12, s16
	s_sub_i32 s16, s12, s15
	s_cmp_ge_u32 s12, s15
	s_cselect_b32 s12, s16, s12
	s_sub_i32 s16, s12, s15
	s_cmp_ge_u32 s12, s15
	s_cselect_b32 s12, s16, s12
	s_xor_b32 s12, s12, s13
	s_sub_i32 s12, s12, s13
	s_add_i32 s12, s12, s14
	v_lshl_or_b32 v2, s12, 8, v153
	v_lshl_add_u64 v[2:3], v[2:3], 2, s[6:7]
	global_load_dword v108, v[2:3], off
.LBB0_1586:
	s_or_b64 exec, exec, s[10:11]
	s_add_u32 s8, s8, s76
	s_addc_u32 s9, s9, s0
	v_mov_b64_e32 v[2:3], 0xaff
	v_cmp_gt_i64_e32 vcc, s[8:9], v[2:3]
	s_cbranch_vccnz .LBB0_1604
	s_and_saveexec_b64 s[10:11], s[2:3]
	s_cbranch_execz .LBB0_1589
	s_ashr_i32 s12, s8, 31
	s_lshr_b32 s12, s12, 29
	s_add_i32 s12, s8, s12
	s_ashr_i32 s13, s12, 3
	s_and_b32 s12, s12, -8
	s_sub_i32 s12, s8, s12
	s_cmp_lt_i32 s12, 0
	s_movk_i32 s14, 0x161
	s_cselect_b32 s14, s14, 0x160
	s_mul_i32 s12, s12, s14
	s_add_i32 s12, s12, s13
	s_mul_hi_i32 s13, s12, 0x2e8ba2e9
	s_lshr_b32 s14, s13, 31
	s_ashr_i32 s13, s13, 4
	s_add_i32 s13, s13, s14
	s_lshl_b32 s14, s13, 2
	s_sub_i32 s15, 0x80, s14
	s_min_i32 s15, s15, 4
	s_abs_i32 s15, s15
	v_cvt_f32_u32_e32 v1, s15
	s_sub_i32 s16, 0, s15
	s_mulk_i32 s13, 0x58
	s_sub_i32 s12, s12, s13
	v_rcp_iflag_f32_e32 v1, v1
	s_ashr_i32 s13, s12, 31
	s_abs_i32 s12, s12
	v_mov_b32_e32 v3, 0
	v_mul_f32_e32 v1, 0x4f7ffffe, v1
	v_cvt_u32_f32_e32 v1, v1
	s_nop 0
	v_readfirstlane_b32 s17, v1
	s_mul_i32 s16, s16, s17
	s_mul_hi_u32 s16, s17, s16
	s_add_i32 s17, s17, s16
	s_mul_hi_u32 s16, s12, s17
	s_mul_i32 s16, s16, s15
	s_sub_i32 s12, s12, s16
	s_sub_i32 s16, s12, s15
	s_cmp_ge_u32 s12, s15
	s_cselect_b32 s12, s16, s12
	s_sub_i32 s16, s12, s15
	s_cmp_ge_u32 s12, s15
	s_cselect_b32 s12, s16, s12
	s_xor_b32 s12, s12, s13
	s_sub_i32 s12, s12, s13
	s_add_i32 s12, s12, s14
	v_lshl_or_b32 v2, s12, 8, v153
	v_lshl_add_u64 v[2:3], v[2:3], 2, s[6:7]
	global_load_dword v109, v[2:3], off
.LBB0_1589:
	s_or_b64 exec, exec, s[10:11]
	s_add_u32 s8, s8, s76
	s_addc_u32 s9, s9, s0
	v_mov_b64_e32 v[2:3], 0xaff
	v_cmp_gt_i64_e32 vcc, s[8:9], v[2:3]
	s_cbranch_vccnz .LBB0_1604
	s_and_saveexec_b64 s[10:11], s[2:3]
	s_cbranch_execz .LBB0_1592
	s_ashr_i32 s12, s8, 31
	s_lshr_b32 s12, s12, 29
	s_add_i32 s12, s8, s12
	s_ashr_i32 s13, s12, 3
	s_and_b32 s12, s12, -8
	s_sub_i32 s12, s8, s12
	s_cmp_lt_i32 s12, 0
	s_movk_i32 s14, 0x161
	s_cselect_b32 s14, s14, 0x160
	s_mul_i32 s12, s12, s14
	s_add_i32 s12, s12, s13
	s_mul_hi_i32 s13, s12, 0x2e8ba2e9
	s_lshr_b32 s14, s13, 31
	s_ashr_i32 s13, s13, 4
	s_add_i32 s13, s13, s14
	s_lshl_b32 s14, s13, 2
	s_sub_i32 s15, 0x80, s14
	s_min_i32 s15, s15, 4
	s_abs_i32 s15, s15
	v_cvt_f32_u32_e32 v1, s15
	s_sub_i32 s16, 0, s15
	s_mulk_i32 s13, 0x58
	s_sub_i32 s12, s12, s13
	v_rcp_iflag_f32_e32 v1, v1
	s_ashr_i32 s13, s12, 31
	s_abs_i32 s12, s12
	v_mov_b32_e32 v3, 0
	v_mul_f32_e32 v1, 0x4f7ffffe, v1
	v_cvt_u32_f32_e32 v1, v1
	s_nop 0
	v_readfirstlane_b32 s17, v1
	s_mul_i32 s16, s16, s17
	s_mul_hi_u32 s16, s17, s16
	s_add_i32 s17, s17, s16
	s_mul_hi_u32 s16, s12, s17
	s_mul_i32 s16, s16, s15
	s_sub_i32 s12, s12, s16
	s_sub_i32 s16, s12, s15
	s_cmp_ge_u32 s12, s15
	s_cselect_b32 s12, s16, s12
	s_sub_i32 s16, s12, s15
	s_cmp_ge_u32 s12, s15
	s_cselect_b32 s12, s16, s12
	s_xor_b32 s12, s12, s13
	s_sub_i32 s12, s12, s13
	s_add_i32 s12, s12, s14
	v_lshl_or_b32 v2, s12, 8, v153
	v_lshl_add_u64 v[2:3], v[2:3], 2, s[6:7]
	global_load_dword v110, v[2:3], off
;     __host__ __device__ bool next(int i, Unit& u) const {
;         const long L = (long)i * G + c; if (L >= nwg) return false;
;         int wgid = (int)L; { const int q = nwg / NXCD, r = nwg % NXCD, xcd = wgid % NXCD, off = wgid / NXCD; wgid = (xcd < r ? xcd * (q + 1) : r * (q + 1) + (xcd - r) * q) + off; }
;         const int nig = WGM * nN, gid = wgid / nig, fm = gid * WGM, gsz = (nM - fm) < WGM ? (nM - fm) : WGM;
;         u.pm = fm + ((wgid % nig) % gsz); u.pn = (wgid % nig) / gsz; u.idx = i; return true;
; template <class Sched>
; __device__ __forceinline__ void rstd_table(LAS float* rs, const float* ss, const Sched& S) {
;     ...
;     for (int i = 0; i < 15 && S.next(i, u); ++i) if (threadIdx.x < BM) rs[i * BM + threadIdx.x] = rsqrtf(ss[u.pm * BM + threadIdx.x] * (1.0f / DM) + NORM_EPS);
.LBB0_1592:
	s_or_b64 exec, exec, s[10:11]
	s_add_u32 s8, s8, s76
	s_addc_u32 s9, s9, s0
	v_mov_b64_e32 v[2:3], 0xaff
	v_cmp_gt_i64_e32 vcc, s[8:9], v[2:3]
	s_cbranch_vccnz .LBB0_1604
	s_and_saveexec_b64 s[10:11], s[2:3]
	s_cbranch_execz .LBB0_1595
	s_ashr_i32 s12, s8, 31
	s_lshr_b32 s12, s12, 29
	s_add_i32 s12, s8, s12
	s_ashr_i32 s13, s12, 3
	s_and_b32 s12, s12, -8
	s_sub_i32 s12, s8, s12
	s_cmp_lt_i32 s12, 0
	s_movk_i32 s14, 0x161
	s_cselect_b32 s14, s14, 0x160
	s_mul_i32 s12, s12, s14
	s_add_i32 s12, s12, s13
	s_mul_hi_i32 s13, s12, 0x2e8ba2e9
	s_lshr_b32 s14, s13, 31
	s_ashr_i32 s13, s13, 4
	s_add_i32 s13, s13, s14
	s_lshl_b32 s14, s13, 2
	s_sub_i32 s15, 0x80, s14
	s_min_i32 s15, s15, 4
	s_abs_i32 s15, s15
	v_cvt_f32_u32_e32 v1, s15
	s_sub_i32 s16, 0, s15
	s_mulk_i32 s13, 0x58
	s_sub_i32 s12, s12, s13
	v_rcp_iflag_f32_e32 v1, v1
	s_ashr_i32 s13, s12, 31
	s_abs_i32 s12, s12
	v_mov_b32_e32 v3, 0
	v_mul_f32_e32 v1, 0x4f7ffffe, v1
	v_cvt_u32_f32_e32 v1, v1
	s_nop 0
	v_readfirstlane_b32 s17, v1
	s_mul_i32 s16, s16, s17
	s_mul_hi_u32 s16, s17, s16
	s_add_i32 s17, s17, s16
	s_mul_hi_u32 s16, s12, s17
	s_mul_i32 s16, s16, s15
	s_sub_i32 s12, s12, s16
	s_sub_i32 s16, s12, s15
	s_cmp_ge_u32 s12, s15
	s_cselect_b32 s12, s16, s12
	s_sub_i32 s16, s12, s15
	s_cmp_ge_u32 s12, s15
	s_cselect_b32 s12, s16, s12
	s_xor_b32 s12, s12, s13
	s_sub_i32 s12, s12, s13
	s_add_i32 s12, s12, s14
	v_lshl_or_b32 v2, s12, 8, v153
	v_lshl_add_u64 v[2:3], v[2:3], 2, s[6:7]
	global_load_dword v111, v[2:3], off
.LBB0_1595:
	s_or_b64 exec, exec, s[10:11]
	s_add_u32 s8, s8, s76
	s_addc_u32 s9, s9, s0
	v_mov_b64_e32 v[2:3], 0xaff
	v_cmp_gt_i64_e32 vcc, s[8:9], v[2:3]
	s_cbranch_vccnz .LBB0_1604
	s_and_saveexec_b64 s[10:11], s[2:3]
	s_cbranch_execz .LBB0_1598
	s_ashr_i32 s12, s8, 31
	s_lshr_b32 s12, s12, 29
	s_add_i32 s12, s8, s12
	s_ashr_i32 s13, s12, 3
	s_and_b32 s12, s12, -8
	s_sub_i32 s12, s8, s12
	s_cmp_lt_i32 s12, 0
	s_movk_i32 s14, 0x161
	s_cselect_b32 s14, s14, 0x160
	s_mul_i32 s12, s12, s14
	s_add_i32 s12, s12, s13
	s_mul_hi_i32 s13, s12, 0x2e8ba2e9
	s_lshr_b32 s14, s13, 31
	s_ashr_i32 s13, s13, 4
	s_add_i32 s13, s13, s14
	s_lshl_b32 s14, s13, 2
	s_sub_i32 s15, 0x80, s14
	s_min_i32 s15, s15, 4
	s_abs_i32 s15, s15
	v_cvt_f32_u32_e32 v1, s15
	s_sub_i32 s16, 0, s15
	s_mulk_i32 s13, 0x58
	s_sub_i32 s12, s12, s13
	v_rcp_iflag_f32_e32 v1, v1
	s_ashr_i32 s13, s12, 31
	s_abs_i32 s12, s12
	v_mov_b32_e32 v3, 0
	v_mul_f32_e32 v1, 0x4f7ffffe, v1
	v_cvt_u32_f32_e32 v1, v1
	s_nop 0
	v_readfirstlane_b32 s17, v1
	s_mul_i32 s16, s16, s17
	s_mul_hi_u32 s16, s17, s16
	s_add_i32 s17, s17, s16
	s_mul_hi_u32 s16, s12, s17
	s_mul_i32 s16, s16, s15
	s_sub_i32 s12, s12, s16
	s_sub_i32 s16, s12, s15
	s_cmp_ge_u32 s12, s15
	s_cselect_b32 s12, s16, s12
	s_sub_i32 s16, s12, s15
	s_cmp_ge_u32 s12, s15
	s_cselect_b32 s12, s16, s12
	s_xor_b32 s12, s12, s13
	s_sub_i32 s12, s12, s13
	s_add_i32 s12, s12, s14
	v_lshl_or_b32 v2, s12, 8, v153
	v_lshl_add_u64 v[2:3], v[2:3], 2, s[6:7]
	global_load_dword v112, v[2:3], off
.LBB0_1598:
	s_or_b64 exec, exec, s[10:11]
	s_add_u32 s8, s8, s76
	s_addc_u32 s9, s9, s0
	v_mov_b64_e32 v[2:3], 0xaff
	v_cmp_gt_i64_e32 vcc, s[8:9], v[2:3]
	s_cbranch_vccnz .LBB0_1604
	s_and_saveexec_b64 s[10:11], s[2:3]
	s_cbranch_execz .LBB0_1601
	s_ashr_i32 s12, s8, 31
	s_lshr_b32 s12, s12, 29
	s_add_i32 s12, s8, s12
	s_ashr_i32 s13, s12, 3
	s_and_b32 s12, s12, -8
	s_sub_i32 s12, s8, s12
	s_cmp_lt_i32 s12, 0
	s_movk_i32 s14, 0x161
	s_cselect_b32 s14, s14, 0x160
	s_mul_i32 s12, s12, s14
	s_add_i32 s12, s12, s13
	s_mul_hi_i32 s13, s12, 0x2e8ba2e9
	s_lshr_b32 s14, s13, 31
	s_ashr_i32 s13, s13, 4
	s_add_i32 s13, s13, s14
	s_lshl_b32 s14, s13, 2
	s_sub_i32 s15, 0x80, s14
	s_min_i32 s15, s15, 4
	s_abs_i32 s15, s15
	v_cvt_f32_u32_e32 v1, s15
	s_sub_i32 s16, 0, s15
	s_mulk_i32 s13, 0x58
	s_sub_i32 s12, s12, s13
	v_rcp_iflag_f32_e32 v1, v1
	s_ashr_i32 s13, s12, 31
	s_abs_i32 s12, s12
	v_mov_b32_e32 v3, 0
	v_mul_f32_e32 v1, 0x4f7ffffe, v1
	v_cvt_u32_f32_e32 v1, v1
	s_nop 0
	v_readfirstlane_b32 s17, v1
	s_mul_i32 s16, s16, s17
	s_mul_hi_u32 s16, s17, s16
	s_add_i32 s17, s17, s16
	s_mul_hi_u32 s16, s12, s17
	s_mul_i32 s16, s16, s15
	s_sub_i32 s12, s12, s16
	s_sub_i32 s16, s12, s15
	s_cmp_ge_u32 s12, s15
	s_cselect_b32 s12, s16, s12
	s_sub_i32 s16, s12, s15
	s_cmp_ge_u32 s12, s15
	s_cselect_b32 s12, s16, s12
	s_xor_b32 s12, s12, s13
	s_sub_i32 s12, s12, s13
	s_add_i32 s12, s12, s14
	v_lshl_or_b32 v2, s12, 8, v153
	v_lshl_add_u64 v[2:3], v[2:3], 2, s[6:7]
	global_load_dword v113, v[2:3], off
.LBB0_1601:
	s_or_b64 exec, exec, s[10:11]
	s_add_u32 s8, s8, s76
	s_addc_u32 s9, s9, s0
	v_mov_b64_e32 v[2:3], 0xb00
	v_cmp_lt_i64_e32 vcc, s[8:9], v[2:3]
	s_and_b64 s[10:11], vcc, s[2:3]
	s_and_saveexec_b64 s[2:3], s[10:11]
	s_cbranch_execz .LBB0_1603
	s_ashr_i32 s9, s8, 31
	s_lshr_b32 s9, s9, 29
	s_add_i32 s9, s8, s9
	s_ashr_i32 s10, s9, 3
	s_and_b32 s9, s9, -8
	s_sub_i32 s8, s8, s9
	s_cmp_lt_i32 s8, 0
	s_movk_i32 s9, 0x161
	s_cselect_b32 s9, s9, 0x160
	s_mul_i32 s8, s8, s9
	s_add_i32 s8, s8, s10
	s_mul_hi_i32 s9, s8, 0x2e8ba2e9
	s_lshr_b32 s10, s9, 31
	s_ashr_i32 s9, s9, 4
	s_add_i32 s9, s9, s10
	s_lshl_b32 s10, s9, 2
	s_sub_i32 s11, 0x80, s10
	s_min_i32 s11, s11, 4
	s_abs_i32 s11, s11
	v_cvt_f32_u32_e32 v1, s11
	s_sub_i32 s12, 0, s11
	s_mulk_i32 s9, 0x58
	s_sub_i32 s8, s8, s9
	v_rcp_iflag_f32_e32 v1, v1
	s_ashr_i32 s9, s8, 31
	s_abs_i32 s8, s8
	v_mov_b32_e32 v3, 0
	v_mul_f32_e32 v1, 0x4f7ffffe, v1
	v_cvt_u32_f32_e32 v1, v1
	s_nop 0
	v_readfirstlane_b32 s13, v1
	s_mul_i32 s12, s12, s13
	s_mul_hi_u32 s12, s13, s12
	s_add_i32 s13, s13, s12
	s_mul_hi_u32 s12, s8, s13
	s_mul_i32 s12, s12, s11
	s_sub_i32 s8, s8, s12
	s_sub_i32 s12, s8, s11
	s_cmp_ge_u32 s8, s11
	s_cselect_b32 s8, s12, s8
	s_sub_i32 s12, s8, s11
	s_cmp_ge_u32 s8, s11
	s_cselect_b32 s8, s12, s8
	s_xor_b32 s8, s8, s9
	s_sub_i32 s8, s8, s9
	s_add_i32 s8, s8, s10
	v_lshl_or_b32 v2, s8, 8, v153
	v_lshl_add_u64 v[2:3], v[2:3], 2, s[6:7]
	global_load_dword v114, v[2:3], off

; template <class Sched>
; __device__ __forceinline__ void rstd_table(LAS float* rs, const float* ss, const Sched& S) {
;     ...
;     for (int i = 0; i < 15 && S.next(i, u); ++i) if (threadIdx.x < BM) rs[i * BM + threadIdx.x] = rsqrtf(ss[u.pm * BM + threadIdx.x] * (1.0f / DM) + NORM_EPS);
.LBB0_1604:
	s_movk_i32 s32, 0x100
	v_cmp_gt_u32_e64 s[24:25], s32, v153
	s_mov_b32 s32, 0x20000
	s_nop 1
	s_and_saveexec_b64 s[36:37], s[24:25]
	v_lshl_add_u32 v115, v153, 2, s32
	s_waitcnt vmcnt(0)
	s_mov_b32 s38, 0x800000
	v_mov_b32_e32 v116, 0x358637bd
	v_fmac_f32_e32 v116, 0x3a800000, v100
	v_mul_f32_e32 v100, 0x4b800000, v116
	v_cmp_gt_f32_e32 vcc, s38, v116
	s_nop 1
	v_cndmask_b32_e32 v100, v116, v100, vcc
	v_rsq_f32_e32 v100, v100
	s_nop 0
	v_mul_f32_e32 v116, 0x45800000, v100
	v_cndmask_b32_e32 v100, v100, v116, vcc
	ds_write_b32 v115, v100
	v_mov_b32_e32 v116, 0x358637bd
	v_fmac_f32_e32 v116, 0x3a800000, v101
	v_mul_f32_e32 v101, 0x4b800000, v116
	v_cmp_gt_f32_e32 vcc, s38, v116
	s_nop 1
	v_cndmask_b32_e32 v101, v116, v101, vcc
	v_rsq_f32_e32 v101, v101
	s_nop 0
	v_mul_f32_e32 v116, 0x45800000, v101
	v_cndmask_b32_e32 v101, v101, v116, vcc
	ds_write_b32 v115, v101 offset:1024
	v_mov_b32_e32 v116, 0x358637bd
	v_fmac_f32_e32 v116, 0x3a800000, v102
	v_mul_f32_e32 v102, 0x4b800000, v116
	v_cmp_gt_f32_e32 vcc, s38, v116
	s_nop 1
	v_cndmask_b32_e32 v102, v116, v102, vcc
	v_rsq_f32_e32 v102, v102
	s_nop 0
	v_mul_f32_e32 v116, 0x45800000, v102
	v_cndmask_b32_e32 v102, v102, v116, vcc
	ds_write_b32 v115, v102 offset:2048
	v_mov_b32_e32 v116, 0x358637bd
	v_fmac_f32_e32 v116, 0x3a800000, v103
	v_mul_f32_e32 v103, 0x4b800000, v116
	v_cmp_gt_f32_e32 vcc, s38, v116
	s_nop 1
	v_cndmask_b32_e32 v103, v116, v103, vcc
	v_rsq_f32_e32 v103, v103
	s_nop 0
	v_mul_f32_e32 v116, 0x45800000, v103
	v_cndmask_b32_e32 v103, v103, v116, vcc
	ds_write_b32 v115, v103 offset:3072
	v_mov_b32_e32 v116, 0x358637bd
	v_fmac_f32_e32 v116, 0x3a800000, v104
	v_mul_f32_e32 v104, 0x4b800000, v116
	v_cmp_gt_f32_e32 vcc, s38, v116
	s_nop 1
	v_cndmask_b32_e32 v104, v116, v104, vcc
	v_rsq_f32_e32 v104, v104
	s_nop 0
	v_mul_f32_e32 v116, 0x45800000, v104
	v_cndmask_b32_e32 v104, v104, v116, vcc
	ds_write_b32 v115, v104 offset:4096
	v_mov_b32_e32 v116, 0x358637bd
	v_fmac_f32_e32 v116, 0x3a800000, v105
	v_mul_f32_e32 v105, 0x4b800000, v116
	v_cmp_gt_f32_e32 vcc, s38, v116
	s_nop 1
	v_cndmask_b32_e32 v105, v116, v105, vcc
	v_rsq_f32_e32 v105, v105
	s_nop 0
	v_mul_f32_e32 v116, 0x45800000, v105
	v_cndmask_b32_e32 v105, v105, v116, vcc
	ds_write_b32 v115, v105 offset:5120
	v_mov_b32_e32 v116, 0x358637bd
	v_fmac_f32_e32 v116, 0x3a800000, v106
	v_mul_f32_e32 v106, 0x4b800000, v116
	v_cmp_gt_f32_e32 vcc, s38, v116
	s_nop 1
	v_cndmask_b32_e32 v106, v116, v106, vcc
	v_rsq_f32_e32 v106, v106
	s_nop 0
	v_mul_f32_e32 v116, 0x45800000, v106
	v_cndmask_b32_e32 v106, v106, v116, vcc
	ds_write_b32 v115, v106 offset:6144
	v_mov_b32_e32 v116, 0x358637bd
	v_fmac_f32_e32 v116, 0x3a800000, v107
	v_mul_f32_e32 v107, 0x4b800000, v116
	v_cmp_gt_f32_e32 vcc, s38, v116
	s_nop 1
	v_cndmask_b32_e32 v107, v116, v107, vcc
	v_rsq_f32_e32 v107, v107
	s_nop 0
	v_mul_f32_e32 v116, 0x45800000, v107
	v_cndmask_b32_e32 v107, v107, v116, vcc
	ds_write_b32 v115, v107 offset:7168
	v_mov_b32_e32 v116, 0x358637bd
	v_fmac_f32_e32 v116, 0x3a800000, v108
	v_mul_f32_e32 v108, 0x4b800000, v116
	v_cmp_gt_f32_e32 vcc, s38, v116
	s_nop 1
	v_cndmask_b32_e32 v108, v116, v108, vcc
	v_rsq_f32_e32 v108, v108
	s_nop 0
	v_mul_f32_e32 v116, 0x45800000, v108
	v_cndmask_b32_e32 v108, v108, v116, vcc
	ds_write_b32 v115, v108 offset:8192
	v_mov_b32_e32 v116, 0x358637bd
	v_fmac_f32_e32 v116, 0x3a800000, v109
	v_mul_f32_e32 v109, 0x4b800000, v116
	v_cmp_gt_f32_e32 vcc, s38, v116
	s_nop 1
	v_cndmask_b32_e32 v109, v116, v109, vcc
	v_rsq_f32_e32 v109, v109
	s_nop 0
	v_mul_f32_e32 v116, 0x45800000, v109
	v_cndmask_b32_e32 v109, v109, v116, vcc
	ds_write_b32 v115, v109 offset:9216
	v_mov_b32_e32 v116, 0x358637bd
	v_fmac_f32_e32 v116, 0x3a800000, v110
	v_mul_f32_e32 v110, 0x4b800000, v116
	v_cmp_gt_f32_e32 vcc, s38, v116
	s_nop 1
	v_cndmask_b32_e32 v110, v116, v110, vcc
	v_rsq_f32_e32 v110, v110
	s_nop 0
	v_mul_f32_e32 v116, 0x45800000, v110
	v_cndmask_b32_e32 v110, v110, v116, vcc
	ds_write_b32 v115, v110 offset:10240
	v_mov_b32_e32 v116, 0x358637bd
	v_fmac_f32_e32 v116, 0x3a800000, v111
	v_mul_f32_e32 v111, 0x4b800000, v116
	v_cmp_gt_f32_e32 vcc, s38, v116
	s_nop 1
	v_cndmask_b32_e32 v111, v116, v111, vcc
	v_rsq_f32_e32 v111, v111
	s_nop 0
	v_mul_f32_e32 v116, 0x45800000, v111
	v_cndmask_b32_e32 v111, v111, v116, vcc
	ds_write_b32 v115, v111 offset:11264
	v_mov_b32_e32 v116, 0x358637bd
	v_fmac_f32_e32 v116, 0x3a800000, v112
	v_mul_f32_e32 v112, 0x4b800000, v116
	v_cmp_gt_f32_e32 vcc, s38, v116
	s_nop 1
	v_cndmask_b32_e32 v112, v116, v112, vcc
	v_rsq_f32_e32 v112, v112
	s_nop 0
	v_mul_f32_e32 v116, 0x45800000, v112
	v_cndmask_b32_e32 v112, v112, v116, vcc
	ds_write_b32 v115, v112 offset:12288
	v_mov_b32_e32 v116, 0x358637bd
	v_fmac_f32_e32 v116, 0x3a800000, v113
	v_mul_f32_e32 v113, 0x4b800000, v116
	v_cmp_gt_f32_e32 vcc, s38, v116
	s_nop 1
	v_cndmask_b32_e32 v113, v116, v113, vcc
	v_rsq_f32_e32 v113, v113
	s_nop 0
	v_mul_f32_e32 v116, 0x45800000, v113
	v_cndmask_b32_e32 v113, v113, v116, vcc
	ds_write_b32 v115, v113 offset:13312
	v_mov_b32_e32 v116, 0x358637bd
	v_fmac_f32_e32 v116, 0x3a800000, v114
	v_mul_f32_e32 v114, 0x4b800000, v116
	v_cmp_gt_f32_e32 vcc, s38, v116
	s_nop 1
	v_cndmask_b32_e32 v114, v116, v114, vcc
	v_rsq_f32_e32 v114, v114
	s_nop 0
	v_mul_f32_e32 v116, 0x45800000, v114
	v_cndmask_b32_e32 v114, v114, v116, vcc
	ds_write_b32 v115, v114 offset:14336
	s_or_b64 exec, exec, s[36:37]
	s_andn2_b64 vcc, exec, s[4:5]
	v_readfirstlane_b32 s3, v153
	s_cbranch_vccnz .LBB0_1620
; #define PG8_STAGE(bufoff, gbase, voff) do { _Pragma("unroll") for (int _i = 0; _i < 2; ++_i) \
;         __builtin_amdgcn_global_load_lds((const unsigned*)((const char*)(gbase) + (voff)[_i]), (LAS unsigned*)(lds + (bufoff) + ldsw + _i * 8192), 16, 0, 0); } while (0)
; #define PG8_BAR __builtin_amdgcn_s_barrier()
; template <class Epi, class Sched, bool ALIGN_EPI>
; __device__ __forceinline__ void gemm_phase(LAS unsigned char* lds, const Gemm g, const Sched& S, const Epi& E) {
;     const int tid = threadIdx.x, wid = __builtin_amdgcn_readfirstlane(tid >> 6), lane = tid & 63, wr = wid >> 2, wc = wid & 3, fr = lane & 15, fq = lane >> 4;
;     const int K = g.K, nt = K / BK;
;     unsigned voffA[2], voffB[2];
; #pragma unroll
;     for (int i = 0; i < 2; ++i) { int R, C; stage_rc(tid * 16 + i * 8192, R, C); const int Rb = (R & ~31) + perm32(R & 31);
;         voffA[i] = (unsigned)(R * g.lda + C) * 2u; voffB[i] = (unsigned)(Rb * g.ldb + C) * 2u; }
;     const size_t kstep = (size_t)(BK * 2);
;     const size_t hstepA = (size_t)HALF * g.lda * 2, hstepB = (size_t)HALF * g.ldb * 2;
;     const size_t tstepA = 2 * hstepA, tstepB = 2 * hstepB;
;     const unsigned ldsw = (unsigned)wid * 1024u;
;     const int aoff = lds_byte(wr * 64 + fr, fq * 8), boff = lds_byte(wc * 32 + fr, fq * 8);
;     ...
;     const char* cA = (const char*)g.A + (size_t)cur.pm * tstepA; const char* cB = (const char*)g.Bt + (size_t)cur.pn * tstepB;
;     PG8_STAGE(PG8_SB(0, 0), cB, voffB); PG8_STAGE(PG8_SB(0, 1), cB + hstepB, voffB); PG8_STAGE(PG8_SA(0, 0), cA, voffA); PG8_STAGE(PG8_SA(0, 1), cA + hstepA, voffA);
;     if (wr == 1) PG8_BAR;
	v_lshrrev_b32_e32 v0, 5, v153
	v_lshrrev_b32_e32 v2, 1, v153
	v_and_b32_e32 v0, 4, v0
	v_bfe_u32 v1, v153, 2, 2
	v_and_b32_e32 v11, 24, v2
	v_or3_b32 v0, v0, v1, v11
	v_lshlrev_b32_e32 v1, 4, v153
	v_add_u32_e32 v8, 0x2000, v1
	s_lshr_b32 s6, s3, 6
	v_lshrrev_b32_e32 v2, 7, v8
	s_movk_i32 s2, 0xe0
	v_and_b32_e32 v4, 32, v153
	s_lshr_b32 s8, s3, 8
	s_lshl_b32 s26, s6, 10
	v_and_or_b32 v3, v2, s2, v0
	v_bitop3_b32 v9, v1, v4, 48 bitop3:0x6c
	v_and_b32_e32 v10, 64, v153
	v_bfe_u32 v12, v153, 2, 4
	s_movk_i32 s2, 0xf0
	s_add_u32 s27, s74, 0x19800000
	v_or_b32_e32 v1, v9, v10
	v_and_or_b32 v2, v2, s2, v12
	s_addc_u32 s28, s75, 0
	v_lshl_or_b32 v130, v2, 11, v1
	v_lshrrev_b32_e32 v2, 3, v153
	s_movk_i32 s2, 0x60
	s_add_u32 s29, s74, 0x1f00000
	v_and_or_b32 v0, v2, s2, v0
	s_movk_i32 s2, 0x70
	s_addc_u32 s30, s75, 0
	v_lshl_or_b32 v132, v0, 11, v1
	v_and_or_b32 v0, v2, s2, v12
	s_lshr_b32 s2, s1, 29
	s_add_i32 s2, s97, s2
	s_ashr_i32 s4, s2, 3
	s_and_b32 s2, s2, -8
	s_sub_i32 s2, s97, s2
	s_cmp_lt_i32 s2, 0
	s_movk_i32 s31, 0x161
	s_cselect_b32 s5, s31, 0x160
	s_mul_i32 s2, s2, s5
	s_add_i32 s2, s2, s4
	s_mul_hi_i32 s4, s2, 0x2e8ba2e9
	s_lshr_b32 s5, s4, 31
	s_ashr_i32 s4, s4, 4
	s_add_i32 s4, s4, s5
	s_lshl_b32 s5, s4, 2
	s_mulk_i32 s4, 0x58
	s_sub_i32 s4, s2, s4
	s_bfe_i32 s2, s4, 0x80000
	s_bfe_u32 s2, s2, 0x2000d
	s_add_i32 s7, s4, s2
	s_bfe_i32 s2, s7, 0x80000
	s_and_b32 s7, s7, 0xfc
	s_sub_i32 s4, s4, s7
	s_sext_i32_i16 s2, s2
	s_sext_i32_i8 s4, s4
	s_lshr_b32 s2, s2, 2
	s_add_i32 s18, s5, s4
	s_ashr_i32 s19, s18, 31
	s_bfe_i64 s[10:11], s[2:3], 0x100000
	s_lshl_b64 s[4:5], s[18:19], 19
	s_lshl_b64 s[10:11], s[10:11], 19
	s_add_u32 s22, s29, s10
	s_addc_u32 s23, s30, s11
	s_add_i32 s19, s26, 0
	s_add_i32 m0, s19, 0x10000
	v_lshl_or_b32 v128, v3, 11, v1
	global_load_lds_dwordx4 v132, s[22:23]
	s_add_i32 m0, s19, 0x12000
	s_add_u32 s10, s22, 0x40000
	global_load_lds_dwordx4 v128, s[22:23]
	s_addc_u32 s11, s23, 0
	s_add_i32 m0, s19, 0x14000
	v_lshl_or_b32 v134, v0, 11, v1
	global_load_lds_dwordx4 v132, s[10:11]
	s_add_i32 m0, s19, 0x16000
	s_add_u32 s20, s27, s4
	s_addc_u32 s21, s28, s5
	s_add_i32 s33, s19, 0x2000
	global_load_lds_dwordx4 v128, s[10:11]
	s_mov_b32 m0, s19
	s_add_u32 s4, s20, 0x40000
	global_load_lds_dwordx4 v134, s[20:21]
	s_mov_b32 m0, s33
	s_addc_u32 s5, s21, 0
	s_add_i32 s34, s19, 0x4000
	global_load_lds_dwordx4 v130, s[20:21]
	s_mov_b32 m0, s34
	s_add_i32 s35, s19, 0x6000
	global_load_lds_dwordx4 v134, s[4:5]
	s_mov_b32 m0, s35
	v_mov_b32_e32 v133, 0
	global_load_lds_dwordx4 v130, s[4:5]
	v_mov_b32_e32 v129, v133
	v_mov_b32_e32 v135, v133
	v_mov_b32_e32 v131, v133
	s_cmp_eq_u32 s8, 1
	s_mov_b32 s43, 0
	v_lshl_add_u64 v[6:7], s[22:23], 0, v[132:133]
	v_lshl_add_u64 v[4:5], s[22:23], 0, v[128:129]
	v_lshl_add_u64 v[0:1], s[20:21], 0, v[134:135]
	s_cselect_b64 s[4:5], -1, 0
	s_cmp_lg_u32 s8, 1
	v_lshl_add_u64 v[2:3], s[20:21], 0, v[130:131]
	s_cbranch_scc1 .LBB0_1607
	s_barrier
